# v15: v8 + hand-written G_OUT and MLPOUT epilogues with XB stores widened to dwordx4 via v_permlane16_swap (64 B per row per store)
# baseline (speedup 1.0000x reference)
;     __device__ __forceinline__ void operator()(const typename AccT<I8>::type (&acc)[2][2][4][2], const Unit& u, int wr, int wc, int fr, int fq) const {
;         const int row0 = u.pm * BM + wr * 64 + fr, col0 = u.pn * BM + wc * 32 + 4 * fq;
;         f32x4 sv[2][2];
;         if (I8) {
; #pragma unroll
;             for (int bj = 0; bj < 2; ++bj)
; #pragma unroll
;                 for (int n = 0; n < 2; ++n) sv[bj][n] = *(const f32x4*)(swc + col0 + bj * HALF + n * 16);
;         }
;         float rsv[8];
; #pragma unroll
;         for (int s = 0; s < 8; ++s) { const int r = row0 + (s >> 2) * HALF + (s & 3) * 16; float rs = 1.f; if (MODE == 1) rs = __builtin_amdgcn_rsqf(rstd[r] * (1.0f / 4096.0f) + 1e-6f); if (I8) rs *= sxr[r]; rsv[s] = rs; }
;         RowIn cur, nxt;
;         load_row(cur, (size_t)row0 * 4096 + col0);
; #pragma unroll
;         for (int s = 0; s < 8; ++s) { const int ai = s >> 2, m = s & 3; const int r = row0 + ai * HALF + m * 16; const size_t off = (size_t)r * 4096 + col0;
;                 if (s + 1 < 8) load_row(nxt, (size_t)(row0 + ((s + 1) >> 2) * HALF + ((s + 1) & 3) * 16) * 4096 + col0);
.LBB0_1724:
	s_lshl_b32 s98, s6, 4
	s_add_i32 s98, s98, s2
	s_sub_i32 s99, s98, 888
	s_cmp_lt_u32 s98, 888
	s_cselect_b32 s98, s98, s99
	s_mov_b32 s99, 0x4200000
	s_cselect_b32 s99, 0x3f600000, s99
	s_lshl_b32 s98, s98, 18
	s_add_u32 s98, s98, s99
	s_add_u32 s98, s96, s98
	s_addc_u32 s99, s97, 0
	v_and_b32_e32 v34, 63, v0
	v_lshrrev_b32_e32 v35, 6, v0
	v_lshlrev_b32_e32 v36, 4, v34
	v_lshl_add_u32 v36, v35, 15, v36
	v_lshrrev_b32_e32 v35, 8, v0
	v_and_b32_e32 v37, 15, v0
	v_lshl_add_u32 v35, v35, 6, v37
	v_lshl_add_u32 v38, s6, 8, v35
	v_bfe_u32 v35, v0, 6, 2
	v_bfe_u32 v39, v0, 4, 2
	v_lshlrev_b32_e32 v35, 5, v35
	v_lshl_add_u32 v35, v39, 2, v35
	v_lshl_add_u32 v35, s2, 8, v35
	v_lshlrev_b32_e32 v40, 13, v38
	v_lshl_add_u32 v40, v35, 1, v40
	v_lshlrev_b32_e32 v41, 2, v38
	v_lshlrev_b32_e32 v37, 3, v39
	v_sub_u32_e32 v40, v40, v37
	v_and_b32_e32 v37, 1, v39
	v_lshl_add_u32 v40, v37, 5, v40
	v_lshrrev_b32_e32 v37, 1, v39
	v_lshl_add_u32 v40, v37, 4, v40
	v_xor_b32_e32 v42, 16, v34
	v_xor_b32_e32 v43, 32, v34
	v_lshlrev_b32_e32 v42, 2, v42
	v_lshlrev_b32_e32 v43, 2, v43
	v_lshlrev_b32_e32 v35, 2, v35
	global_load_dwordx4 v[162:165], v35, s[14:15] offset:0
	global_load_dwordx4 v[166:169], v35, s[14:15] offset:64
	global_load_dwordx4 v[170:173], v35, s[14:15] offset:512
	global_load_dwordx4 v[218:221], v35, s[14:15] offset:576
	global_load_dword v222, v41, s[16:17] offset:0
	global_load_dword v223, v41, s[16:17] offset:64
	global_load_dword v224, v41, s[16:17] offset:128
	global_load_dword v225, v41, s[16:17] offset:192
	global_load_dword v226, v41, s[16:17] offset:512
	global_load_dword v227, v41, s[16:17] offset:576
	global_load_dword v228, v41, s[16:17] offset:640
	global_load_dword v229, v41, s[16:17] offset:704
	v_lshl_add_u32 v44, v38, 14, v35
	v_cmp_eq_u32_e64 s[6:7], 0, v39
	v_readlane_b32 s68, v254, 40
	v_readlane_b32 s69, v254, 41
	global_load_dwordx4 v[146:149], v44, s[64:65] offset:0
	global_load_dwordx4 v[150:153], v44, s[64:65] offset:64
	global_load_dwordx4 v[154:157], v44, s[64:65] offset:512
	global_load_dwordx4 v[158:161], v44, s[64:65] offset:576
	v_add_u32_e32 v45, 0x40000, v44
	global_load_dwordx4 v[186:189], v45, s[64:65] offset:0
	global_load_dwordx4 v[190:193], v45, s[64:65] offset:64
	global_load_dwordx4 v[194:197], v45, s[64:65] offset:512
	global_load_dwordx4 v[198:201], v45, s[64:65] offset:576
	v_add_u32_e32 v45, 0x80000, v44
	global_load_dwordx4 v[202:205], v45, s[64:65] offset:0
	global_load_dwordx4 v[206:209], v45, s[64:65] offset:64
	global_load_dwordx4 v[210:213], v45, s[64:65] offset:512
	global_load_dwordx4 v[214:217], v45, s[64:65] offset:576
	v_cvt_f32_i32_e32 v142, v142
	v_cvt_f32_i32_e32 v143, v143
	v_cvt_f32_i32_e32 v144, v144
	v_cvt_f32_i32_e32 v145, v145
	v_cvt_f32_i32_e32 v138, v138
	v_cvt_f32_i32_e32 v139, v139
	v_cvt_f32_i32_e32 v140, v140
	v_cvt_f32_i32_e32 v141, v141
	v_cvt_f32_i32_e32 v134, v134
	v_cvt_f32_i32_e32 v135, v135
	v_cvt_f32_i32_e32 v136, v136
	v_cvt_f32_i32_e32 v137, v137
	v_cvt_f32_i32_e32 v130, v130
	v_cvt_f32_i32_e32 v131, v131
	v_cvt_f32_i32_e32 v132, v132
	v_cvt_f32_i32_e32 v133, v133
	v_cvt_f32_i32_e32 v126, v126
	v_cvt_f32_i32_e32 v127, v127
	v_cvt_f32_i32_e32 v128, v128
	v_cvt_f32_i32_e32 v129, v129
	v_cvt_f32_i32_e32 v122, v122
	v_cvt_f32_i32_e32 v123, v123
	v_cvt_f32_i32_e32 v124, v124
	v_cvt_f32_i32_e32 v125, v125
	v_cvt_f32_i32_e32 v118, v118
	v_cvt_f32_i32_e32 v119, v119
	v_cvt_f32_i32_e32 v120, v120
	v_cvt_f32_i32_e32 v121, v121
	v_cvt_f32_i32_e32 v114, v114
	v_cvt_f32_i32_e32 v115, v115
	v_cvt_f32_i32_e32 v116, v116
	v_cvt_f32_i32_e32 v117, v117
	v_cvt_f32_i32_e32 v110, v110
	v_cvt_f32_i32_e32 v111, v111
	v_cvt_f32_i32_e32 v112, v112
	v_cvt_f32_i32_e32 v113, v113
	v_cvt_f32_i32_e32 v106, v106
	v_cvt_f32_i32_e32 v107, v107
	v_cvt_f32_i32_e32 v108, v108
	v_cvt_f32_i32_e32 v109, v109
	v_cvt_f32_i32_e32 v102, v102
	v_cvt_f32_i32_e32 v103, v103
	v_cvt_f32_i32_e32 v104, v104
	v_cvt_f32_i32_e32 v105, v105
	v_cvt_f32_i32_e32 v98, v98
	v_cvt_f32_i32_e32 v99, v99
	v_cvt_f32_i32_e32 v100, v100
	v_cvt_f32_i32_e32 v101, v101
	v_cvt_f32_i32_e32 v94, v94
	v_cvt_f32_i32_e32 v95, v95
	v_cvt_f32_i32_e32 v96, v96
	v_cvt_f32_i32_e32 v97, v97
	v_cvt_f32_i32_e32 v90, v90
	v_cvt_f32_i32_e32 v91, v91
	v_cvt_f32_i32_e32 v92, v92
	v_cvt_f32_i32_e32 v93, v93
	v_cvt_f32_i32_e32 v86, v86
	v_cvt_f32_i32_e32 v87, v87
	v_cvt_f32_i32_e32 v88, v88
	v_cvt_f32_i32_e32 v89, v89
	v_cvt_f32_i32_e32 v82, v82
	v_cvt_f32_i32_e32 v83, v83
	v_cvt_f32_i32_e32 v84, v84
	v_cvt_f32_i32_e32 v85, v85
	v_cvt_f32_i32_e32 v78, v78
	v_cvt_f32_i32_e32 v79, v79
	v_cvt_f32_i32_e32 v80, v80
	v_cvt_f32_i32_e32 v81, v81
	v_cvt_f32_i32_e32 v74, v74
	v_cvt_f32_i32_e32 v75, v75
	v_cvt_f32_i32_e32 v76, v76
	v_cvt_f32_i32_e32 v77, v77
	v_cvt_f32_i32_e32 v70, v70
	v_cvt_f32_i32_e32 v71, v71
	v_cvt_f32_i32_e32 v72, v72
	v_cvt_f32_i32_e32 v73, v73
	v_cvt_f32_i32_e32 v66, v66
	v_cvt_f32_i32_e32 v67, v67
	v_cvt_f32_i32_e32 v68, v68
	v_cvt_f32_i32_e32 v69, v69
	v_cvt_f32_i32_e32 v58, v58
	v_cvt_f32_i32_e32 v59, v59
	v_cvt_f32_i32_e32 v60, v60
	v_cvt_f32_i32_e32 v61, v61
	v_cvt_f32_i32_e32 v54, v54
	v_cvt_f32_i32_e32 v55, v55
	v_cvt_f32_i32_e32 v56, v56
	v_cvt_f32_i32_e32 v57, v57
	v_cvt_f32_i32_e32 v50, v50
	v_cvt_f32_i32_e32 v51, v51
	v_cvt_f32_i32_e32 v52, v52
	v_cvt_f32_i32_e32 v53, v53
	v_cvt_f32_i32_e32 v46, v46
	v_cvt_f32_i32_e32 v47, v47
	v_cvt_f32_i32_e32 v48, v48
	v_cvt_f32_i32_e32 v49, v49
	v_cvt_f32_i32_e32 v30, v30
	v_cvt_f32_i32_e32 v31, v31
	v_cvt_f32_i32_e32 v32, v32
	v_cvt_f32_i32_e32 v33, v33
	v_cvt_f32_i32_e32 v26, v26
	v_cvt_f32_i32_e32 v27, v27
	v_cvt_f32_i32_e32 v28, v28
	v_cvt_f32_i32_e32 v29, v29
	v_cvt_f32_i32_e32 v22, v22
	v_cvt_f32_i32_e32 v23, v23
	v_cvt_f32_i32_e32 v24, v24
	v_cvt_f32_i32_e32 v25, v25
	v_cvt_f32_i32_e32 v18, v18
	v_cvt_f32_i32_e32 v19, v19
	v_cvt_f32_i32_e32 v20, v20
	v_cvt_f32_i32_e32 v21, v21
	v_cvt_f32_i32_e32 v14, v14
	v_cvt_f32_i32_e32 v15, v15
	v_cvt_f32_i32_e32 v16, v16
	v_cvt_f32_i32_e32 v17, v17
	v_cvt_f32_i32_e32 v10, v10
	v_cvt_f32_i32_e32 v11, v11
	v_cvt_f32_i32_e32 v12, v12
	v_cvt_f32_i32_e32 v13, v13
	v_cvt_f32_i32_e32 v6, v6
	v_cvt_f32_i32_e32 v7, v7
	v_cvt_f32_i32_e32 v8, v8
	v_cvt_f32_i32_e32 v9, v9
	v_cvt_f32_i32_e32 v2, v2
	v_cvt_f32_i32_e32 v3, v3
	v_cvt_f32_i32_e32 v4, v4
	v_cvt_f32_i32_e32 v5, v5
	s_waitcnt vmcnt(12)
; __device__ __forceinline__ unsigned cvt_pk_bf16(float lo, float hi) { unsigned r; asm volatile("s_nop 0\n\tv_cvt_pk_bf16_f32 %0, %1, %2" : "=v"(r) : "v"(lo), "v"(hi)); return r; }
; __device__ __forceinline__ f32x4 sig4(const f32x4 v) { return (f32x4){sigmoidf_(v[0]), sigmoidf_(v[1]), sigmoidf_(v[2]), sigmoidf_(v[3])}; }
;     __device__ __forceinline__ void operator()(const typename AccT<I8>::type (&acc)[2][2][4][2], const Unit& u, int wr, int wc, int fr, int fq) const {
;     ...
;         for (int s = 0; s < 8; ++s) { const int ai = s >> 2, m = s & 3; const int r = row0 + ai * HALF + m * 16; const size_t off = (size_t)r * 4096 + col0;
;                 if (s + 1 < 8) load_row(nxt, (size_t)(row0 + ((s + 1) >> 2) * HALF + ((s + 1) & 3) * 16) * 4096 + col0);
;                 const float rs = rsv[s];
;                 float ss = 0.f, mx = 0.f;
; #pragma unroll
;                 for (int bj = 0; bj < 2; ++bj)
; #pragma unroll
;                     for (int n = 0; n < 2; ++n) { const size_t o = off + bj * HALF + n * 16; const f32x4 b = cur.b[bj][n]; f32x4 v;
;                         if constexpr (I8) v = __builtin_convertvector(acc[ai][bj][m][n], f32x4) * rs * sv[bj][n]; else v = acc[ai][bj][m][n];
;                         if (MODE == 1) { const u32x2 pw = cur.pw[bj][n]; const f32x4 pp = (f32x4){bf_lo(pw.x), bf_hi(pw.x), bf_lo(pw.y), bf_hi(pw.y)}; v = sig4(I8 ? v : v * rs) * pp; }
;                         const f32x4 x = b + v; *(f32x4*)(out + o) = x;
;                         if (MODE == 0 && XB) { u32x2 w; w.x = cvt_pk_bf16(x[0], x[1]); w.y = cvt_pk_bf16(x[2], x[3]); *(u32x2*)(XB + o) = w; ss += (x[0] * x[0] + x[1] * x[1]) + (x[2] * x[2] + x[3] * x[3]);
;                             if (RM) mx = fmaxf(fmaxf(mx, fmaxf(fabsf(x[0]), fabsf(x[1]))), fmaxf(fabsf(x[2]), fabsf(x[3]))); } }
;                 if (MODE == 0 && XB) { ss += __shfl_xor(ss, 16); ss += __shfl_xor(ss, 32); if (fq == 0) unsafeAtomicAdd(SS + r, ss);
;                     if (RM) { mx = fmaxf(mx, __shfl_xor(mx, 16)); mx = fmaxf(mx, __shfl_xor(mx, 32)); if (fq == 0) atomicMax(RM + r, __builtin_bit_cast(unsigned, mx)); } }
	s_waitcnt vmcnt(8)
	v_pk_mul_f32 v[142:143], v[222:223], v[142:143] op_sel:[0,0] op_sel_hi:[0,1]
	v_pk_mul_f32 v[144:145], v[222:223], v[144:145] op_sel:[0,0] op_sel_hi:[0,1]
	v_pk_fma_f32 v[142:143], v[162:163], v[142:143], v[146:147]
	v_pk_fma_f32 v[144:145], v[164:165], v[144:145], v[148:149]
	v_pk_mul_f32 v[138:139], v[222:223], v[138:139] op_sel:[0,0] op_sel_hi:[0,1]
	v_pk_mul_f32 v[140:141], v[222:223], v[140:141] op_sel:[0,0] op_sel_hi:[0,1]
	v_pk_fma_f32 v[138:139], v[166:167], v[138:139], v[150:151]
	v_pk_fma_f32 v[140:141], v[168:169], v[140:141], v[152:153]
	v_pk_mul_f32 v[134:135], v[222:223], v[134:135] op_sel:[0,0] op_sel_hi:[0,1]
	v_pk_mul_f32 v[136:137], v[222:223], v[136:137] op_sel:[0,0] op_sel_hi:[0,1]
	v_pk_fma_f32 v[134:135], v[170:171], v[134:135], v[154:155]
	v_pk_fma_f32 v[136:137], v[172:173], v[136:137], v[156:157]
	v_pk_mul_f32 v[130:131], v[222:223], v[130:131] op_sel:[0,0] op_sel_hi:[0,1]
	v_pk_mul_f32 v[132:133], v[222:223], v[132:133] op_sel:[0,0] op_sel_hi:[0,1]
	v_pk_fma_f32 v[130:131], v[218:219], v[130:131], v[158:159]
	v_pk_fma_f32 v[132:133], v[220:221], v[132:133], v[160:161]
	v_add_u32_e32 v45, 0xc0000, v44
	global_load_dwordx4 v[146:149], v45, s[64:65] offset:0
	global_load_dwordx4 v[150:153], v45, s[64:65] offset:64
	global_load_dwordx4 v[154:157], v45, s[64:65] offset:512
	global_load_dwordx4 v[158:161], v45, s[64:65] offset:576
	global_store_dwordx4 v36, v[142:145], s[98:99] offset:0
	v_cvt_pk_bf16_f32 v240, v142, v143
	v_cvt_pk_bf16_f32 v241, v144, v145
	v_mul_f32_e32 v230, v143, v143
	v_mul_f32_e32 v231, v145, v145
	v_fmac_f32_e32 v230, v142, v142
	v_fmac_f32_e32 v231, v144, v144
	v_add_f32_e32 v63, v230, v231
	v_max3_f32 v64, |v142|, |v143|, 0
	v_max3_f32 v64, |v144|, |v145|, v64
	global_store_dwordx4 v36, v[138:141], s[98:99] offset:1024
	v_cvt_pk_bf16_f32 v242, v138, v139
	v_cvt_pk_bf16_f32 v243, v140, v141
	v_mul_f32_e32 v230, v139, v139
	v_mul_f32_e32 v231, v141, v141
	v_fmac_f32_e32 v230, v138, v138
	v_fmac_f32_e32 v231, v140, v140
	v_permlane16_swap_b32_e32 v240, v242
	v_permlane16_swap_b32_e32 v241, v243
	v_add_f32_e32 v230, v230, v231
	v_add_f32_e32 v63, v63, v230
	v_max3_f32 v64, |v138|, |v139|, v64
	v_max3_f32 v64, |v140|, |v141|, v64
	global_store_dwordx4 v40, v[240:243], s[68:69] offset:0
	global_store_dwordx4 v36, v[134:137], s[98:99] offset:2048
	v_cvt_pk_bf16_f32 v244, v134, v135
	v_cvt_pk_bf16_f32 v245, v136, v137
	v_mul_f32_e32 v230, v135, v135
	v_mul_f32_e32 v231, v137, v137
	v_fmac_f32_e32 v230, v134, v134
	v_fmac_f32_e32 v231, v136, v136
	v_add_f32_e32 v230, v230, v231
	v_add_f32_e32 v63, v63, v230
	v_max3_f32 v64, |v134|, |v135|, v64
	v_max3_f32 v64, |v136|, |v137|, v64
	global_store_dwordx4 v36, v[130:133], s[98:99] offset:3072
	v_cvt_pk_bf16_f32 v246, v130, v131
	v_cvt_pk_bf16_f32 v247, v132, v133
	v_mul_f32_e32 v230, v131, v131
	v_mul_f32_e32 v231, v133, v133
	v_fmac_f32_e32 v230, v130, v130
	v_fmac_f32_e32 v231, v132, v132
	v_permlane16_swap_b32_e32 v244, v246
	v_permlane16_swap_b32_e32 v245, v247
	v_add_f32_e32 v230, v230, v231
	v_add_f32_e32 v63, v63, v230
	v_max3_f32 v64, |v130|, |v131|, v64
	v_max3_f32 v64, |v132|, |v133|, v64
	global_store_dwordx4 v40, v[244:247], s[68:69] offset:256
	ds_bpermute_b32 v238, v42, v63
	ds_bpermute_b32 v239, v42, v64
	s_waitcnt lgkmcnt(0)
	v_add_f32_e32 v63, v63, v238
	v_max_f32_e32 v64, v64, v239
	ds_bpermute_b32 v238, v43, v63
	ds_bpermute_b32 v239, v43, v64
	s_waitcnt lgkmcnt(0)
	v_add_f32_e32 v63, v63, v238
	v_max_f32_e32 v64, v64, v239
	s_mov_b64 exec, s[6:7]
	global_atomic_add_f32 v41, v63, s[10:11] offset:0
	global_atomic_umax v41, v64, s[12:13] offset:0
	s_mov_b64 exec, -1
	s_waitcnt vmcnt(16)
	v_pk_mul_f32 v[126:127], v[222:223], v[126:127] op_sel:[1,0] op_sel_hi:[1,1]
	v_pk_mul_f32 v[128:129], v[222:223], v[128:129] op_sel:[1,0] op_sel_hi:[1,1]
	v_pk_fma_f32 v[126:127], v[162:163], v[126:127], v[186:187]
	v_pk_fma_f32 v[128:129], v[164:165], v[128:129], v[188:189]
	v_pk_mul_f32 v[122:123], v[222:223], v[122:123] op_sel:[1,0] op_sel_hi:[1,1]
	v_pk_mul_f32 v[124:125], v[222:223], v[124:125] op_sel:[1,0] op_sel_hi:[1,1]
	v_pk_fma_f32 v[122:123], v[166:167], v[122:123], v[190:191]
	v_pk_fma_f32 v[124:125], v[168:169], v[124:125], v[192:193]
	v_pk_mul_f32 v[118:119], v[222:223], v[118:119] op_sel:[1,0] op_sel_hi:[1,1]
	v_pk_mul_f32 v[120:121], v[222:223], v[120:121] op_sel:[1,0] op_sel_hi:[1,1]
	v_pk_fma_f32 v[118:119], v[170:171], v[118:119], v[194:195]
	v_pk_fma_f32 v[120:121], v[172:173], v[120:121], v[196:197]
	v_pk_mul_f32 v[114:115], v[222:223], v[114:115] op_sel:[1,0] op_sel_hi:[1,1]
	v_pk_mul_f32 v[116:117], v[222:223], v[116:117] op_sel:[1,0] op_sel_hi:[1,1]
	v_pk_fma_f32 v[114:115], v[218:219], v[114:115], v[198:199]
	v_pk_fma_f32 v[116:117], v[220:221], v[116:117], v[200:201]
	v_add_u32_e32 v45, 0x200000, v44
	global_load_dwordx4 v[186:189], v45, s[64:65] offset:0
	global_load_dwordx4 v[190:193], v45, s[64:65] offset:64
	global_load_dwordx4 v[194:197], v45, s[64:65] offset:512
	global_load_dwordx4 v[198:201], v45, s[64:65] offset:576
	v_add_u32_e32 v62, 0x1000, v36
	v_add_u32_e32 v65, 0x20000, v40
	global_store_dwordx4 v62, v[126:129], s[98:99] offset:0
	v_cvt_pk_bf16_f32 v240, v126, v127
	v_cvt_pk_bf16_f32 v241, v128, v129
	v_mul_f32_e32 v230, v127, v127
	v_mul_f32_e32 v231, v129, v129
	v_fmac_f32_e32 v230, v126, v126
	v_fmac_f32_e32 v231, v128, v128
	v_add_f32_e32 v63, v230, v231
	v_max3_f32 v64, |v126|, |v127|, 0
	v_max3_f32 v64, |v128|, |v129|, v64
	global_store_dwordx4 v62, v[122:125], s[98:99] offset:1024
	v_cvt_pk_bf16_f32 v242, v122, v123
	v_cvt_pk_bf16_f32 v243, v124, v125
	v_mul_f32_e32 v230, v123, v123
	v_mul_f32_e32 v231, v125, v125
	v_fmac_f32_e32 v230, v122, v122
	v_fmac_f32_e32 v231, v124, v124
	v_permlane16_swap_b32_e32 v240, v242
	v_permlane16_swap_b32_e32 v241, v243
	v_add_f32_e32 v230, v230, v231
	v_add_f32_e32 v63, v63, v230
	v_max3_f32 v64, |v122|, |v123|, v64
	v_max3_f32 v64, |v124|, |v125|, v64
	global_store_dwordx4 v65, v[240:243], s[68:69] offset:0
	global_store_dwordx4 v62, v[118:121], s[98:99] offset:2048
	v_cvt_pk_bf16_f32 v244, v118, v119
	v_cvt_pk_bf16_f32 v245, v120, v121
	v_mul_f32_e32 v230, v119, v119
	v_mul_f32_e32 v231, v121, v121
	v_fmac_f32_e32 v230, v118, v118
	v_fmac_f32_e32 v231, v120, v120
	v_add_f32_e32 v230, v230, v231
	v_add_f32_e32 v63, v63, v230
	v_max3_f32 v64, |v118|, |v119|, v64
	v_max3_f32 v64, |v120|, |v121|, v64
	global_store_dwordx4 v62, v[114:117], s[98:99] offset:3072
	v_cvt_pk_bf16_f32 v246, v114, v115
	v_cvt_pk_bf16_f32 v247, v116, v117
	v_mul_f32_e32 v230, v115, v115
	v_mul_f32_e32 v231, v117, v117
	v_fmac_f32_e32 v230, v114, v114
	v_fmac_f32_e32 v231, v116, v116
	v_permlane16_swap_b32_e32 v244, v246
	v_permlane16_swap_b32_e32 v245, v247
	v_add_f32_e32 v230, v230, v231
	v_add_f32_e32 v63, v63, v230
	v_max3_f32 v64, |v114|, |v115|, v64
	v_max3_f32 v64, |v116|, |v117|, v64
	global_store_dwordx4 v65, v[244:247], s[68:69] offset:256
	ds_bpermute_b32 v238, v42, v63
	ds_bpermute_b32 v239, v42, v64
	s_waitcnt lgkmcnt(0)
; __device__ __forceinline__ unsigned cvt_pk_bf16(float lo, float hi) { unsigned r; asm volatile("s_nop 0\n\tv_cvt_pk_bf16_f32 %0, %1, %2" : "=v"(r) : "v"(lo), "v"(hi)); return r; }
; __device__ __forceinline__ f32x4 sig4(const f32x4 v) { return (f32x4){sigmoidf_(v[0]), sigmoidf_(v[1]), sigmoidf_(v[2]), sigmoidf_(v[3])}; }
;     __device__ __forceinline__ void operator()(const typename AccT<I8>::type (&acc)[2][2][4][2], const Unit& u, int wr, int wc, int fr, int fq) const {
;     ...
;         for (int s = 0; s < 8; ++s) { const int ai = s >> 2, m = s & 3; const int r = row0 + ai * HALF + m * 16; const size_t off = (size_t)r * 4096 + col0;
;                 if (s + 1 < 8) load_row(nxt, (size_t)(row0 + ((s + 1) >> 2) * HALF + ((s + 1) & 3) * 16) * 4096 + col0);
;                 const float rs = rsv[s];
;                 float ss = 0.f, mx = 0.f;
; #pragma unroll
;                 for (int bj = 0; bj < 2; ++bj)
; #pragma unroll
;                     for (int n = 0; n < 2; ++n) { const size_t o = off + bj * HALF + n * 16; const f32x4 b = cur.b[bj][n]; f32x4 v;
;                         if constexpr (I8) v = __builtin_convertvector(acc[ai][bj][m][n], f32x4) * rs * sv[bj][n]; else v = acc[ai][bj][m][n];
;                         if (MODE == 1) { const u32x2 pw = cur.pw[bj][n]; const f32x4 pp = (f32x4){bf_lo(pw.x), bf_hi(pw.x), bf_lo(pw.y), bf_hi(pw.y)}; v = sig4(I8 ? v : v * rs) * pp; }
;                         const f32x4 x = b + v; *(f32x4*)(out + o) = x;
;                         if (MODE == 0 && XB) { u32x2 w; w.x = cvt_pk_bf16(x[0], x[1]); w.y = cvt_pk_bf16(x[2], x[3]); *(u32x2*)(XB + o) = w; ss += (x[0] * x[0] + x[1] * x[1]) + (x[2] * x[2] + x[3] * x[3]);
;                             if (RM) mx = fmaxf(fmaxf(mx, fmaxf(fabsf(x[0]), fabsf(x[1]))), fmaxf(fabsf(x[2]), fabsf(x[3]))); } }
;                 if (MODE == 0 && XB) { ss += __shfl_xor(ss, 16); ss += __shfl_xor(ss, 32); if (fq == 0) unsafeAtomicAdd(SS + r, ss);
;                     if (RM) { mx = fmaxf(mx, __shfl_xor(mx, 16)); mx = fmaxf(mx, __shfl_xor(mx, 32)); if (fq == 0) atomicMax(RM + r, __builtin_bit_cast(unsigned, mx)); } }
;                 cur = nxt; }
	v_add_f32_e32 v63, v63, v238
	v_max_f32_e32 v64, v64, v239
	ds_bpermute_b32 v238, v43, v63
	ds_bpermute_b32 v239, v43, v64
	s_waitcnt lgkmcnt(0)
	v_add_f32_e32 v63, v63, v238
	v_max_f32_e32 v64, v64, v239
	s_mov_b64 exec, s[6:7]
	global_atomic_add_f32 v41, v63, s[10:11] offset:64
	global_atomic_umax v41, v64, s[12:13] offset:64
	s_mov_b64 exec, -1
	s_waitcnt vmcnt(24)
	v_pk_mul_f32 v[110:111], v[224:225], v[110:111] op_sel:[0,0] op_sel_hi:[0,1]
	v_pk_mul_f32 v[112:113], v[224:225], v[112:113] op_sel:[0,0] op_sel_hi:[0,1]
	v_pk_fma_f32 v[110:111], v[162:163], v[110:111], v[202:203]
	v_pk_fma_f32 v[112:113], v[164:165], v[112:113], v[204:205]
	v_pk_mul_f32 v[106:107], v[224:225], v[106:107] op_sel:[0,0] op_sel_hi:[0,1]
	v_pk_mul_f32 v[108:109], v[224:225], v[108:109] op_sel:[0,0] op_sel_hi:[0,1]
	v_pk_fma_f32 v[106:107], v[166:167], v[106:107], v[206:207]
	v_pk_fma_f32 v[108:109], v[168:169], v[108:109], v[208:209]
	v_pk_mul_f32 v[102:103], v[224:225], v[102:103] op_sel:[0,0] op_sel_hi:[0,1]
	v_pk_mul_f32 v[104:105], v[224:225], v[104:105] op_sel:[0,0] op_sel_hi:[0,1]
	v_pk_fma_f32 v[102:103], v[170:171], v[102:103], v[210:211]
	v_pk_fma_f32 v[104:105], v[172:173], v[104:105], v[212:213]
	v_pk_mul_f32 v[98:99], v[224:225], v[98:99] op_sel:[0,0] op_sel_hi:[0,1]
	v_pk_mul_f32 v[100:101], v[224:225], v[100:101] op_sel:[0,0] op_sel_hi:[0,1]
	v_pk_fma_f32 v[98:99], v[218:219], v[98:99], v[214:215]
	v_pk_fma_f32 v[100:101], v[220:221], v[100:101], v[216:217]
	v_add_u32_e32 v45, 0x240000, v44
	global_load_dwordx4 v[202:205], v45, s[64:65] offset:0
	global_load_dwordx4 v[206:209], v45, s[64:65] offset:64
	global_load_dwordx4 v[210:213], v45, s[64:65] offset:512
	global_load_dwordx4 v[214:217], v45, s[64:65] offset:576
	v_add_u32_e32 v62, 0x2000, v36
	v_add_u32_e32 v65, 0x40000, v40
	global_store_dwordx4 v62, v[110:113], s[98:99] offset:0
	v_cvt_pk_bf16_f32 v240, v110, v111
	v_cvt_pk_bf16_f32 v241, v112, v113
	v_mul_f32_e32 v230, v111, v111
	v_mul_f32_e32 v231, v113, v113
	v_fmac_f32_e32 v230, v110, v110
	v_fmac_f32_e32 v231, v112, v112
	v_add_f32_e32 v63, v230, v231
	v_max3_f32 v64, |v110|, |v111|, 0
	v_max3_f32 v64, |v112|, |v113|, v64
	global_store_dwordx4 v62, v[106:109], s[98:99] offset:1024
	v_cvt_pk_bf16_f32 v242, v106, v107
	v_cvt_pk_bf16_f32 v243, v108, v109
	v_mul_f32_e32 v230, v107, v107
	v_mul_f32_e32 v231, v109, v109
	v_fmac_f32_e32 v230, v106, v106
	v_fmac_f32_e32 v231, v108, v108
	v_permlane16_swap_b32_e32 v240, v242
	v_permlane16_swap_b32_e32 v241, v243
	v_add_f32_e32 v230, v230, v231
	v_add_f32_e32 v63, v63, v230
	v_max3_f32 v64, |v106|, |v107|, v64
	v_max3_f32 v64, |v108|, |v109|, v64
	global_store_dwordx4 v65, v[240:243], s[68:69] offset:0
	global_store_dwordx4 v62, v[102:105], s[98:99] offset:2048
	v_cvt_pk_bf16_f32 v244, v102, v103
	v_cvt_pk_bf16_f32 v245, v104, v105
	v_mul_f32_e32 v230, v103, v103
	v_mul_f32_e32 v231, v105, v105
	v_fmac_f32_e32 v230, v102, v102
	v_fmac_f32_e32 v231, v104, v104
	v_add_f32_e32 v230, v230, v231
	v_add_f32_e32 v63, v63, v230
	v_max3_f32 v64, |v102|, |v103|, v64
	v_max3_f32 v64, |v104|, |v105|, v64
	global_store_dwordx4 v62, v[98:101], s[98:99] offset:3072
	v_cvt_pk_bf16_f32 v246, v98, v99
	v_cvt_pk_bf16_f32 v247, v100, v101
	v_mul_f32_e32 v230, v99, v99
	v_mul_f32_e32 v231, v101, v101
	v_fmac_f32_e32 v230, v98, v98
	v_fmac_f32_e32 v231, v100, v100
	v_permlane16_swap_b32_e32 v244, v246
	v_permlane16_swap_b32_e32 v245, v247
	v_add_f32_e32 v230, v230, v231
	v_add_f32_e32 v63, v63, v230
	v_max3_f32 v64, |v98|, |v99|, v64
	v_max3_f32 v64, |v100|, |v101|, v64
	global_store_dwordx4 v65, v[244:247], s[68:69] offset:256
	ds_bpermute_b32 v238, v42, v63
	ds_bpermute_b32 v239, v42, v64
	s_waitcnt lgkmcnt(0)
	v_add_f32_e32 v63, v63, v238
	v_max_f32_e32 v64, v64, v239
	ds_bpermute_b32 v238, v43, v63
	ds_bpermute_b32 v239, v43, v64
	s_waitcnt lgkmcnt(0)
	v_add_f32_e32 v63, v63, v238
	v_max_f32_e32 v64, v64, v239
	s_mov_b64 exec, s[6:7]
	global_atomic_add_f32 v41, v63, s[10:11] offset:128
	global_atomic_umax v41, v64, s[12:13] offset:128
	s_mov_b64 exec, -1
	s_waitcnt vmcnt(32)
	v_pk_mul_f32 v[94:95], v[224:225], v[94:95] op_sel:[1,0] op_sel_hi:[1,1]
	v_pk_mul_f32 v[96:97], v[224:225], v[96:97] op_sel:[1,0] op_sel_hi:[1,1]
	v_pk_fma_f32 v[94:95], v[162:163], v[94:95], v[146:147]
	v_pk_fma_f32 v[96:97], v[164:165], v[96:97], v[148:149]
	v_pk_mul_f32 v[90:91], v[224:225], v[90:91] op_sel:[1,0] op_sel_hi:[1,1]
	v_pk_mul_f32 v[92:93], v[224:225], v[92:93] op_sel:[1,0] op_sel_hi:[1,1]
	v_pk_fma_f32 v[90:91], v[166:167], v[90:91], v[150:151]
	v_pk_fma_f32 v[92:93], v[168:169], v[92:93], v[152:153]
	v_pk_mul_f32 v[86:87], v[224:225], v[86:87] op_sel:[1,0] op_sel_hi:[1,1]
	v_pk_mul_f32 v[88:89], v[224:225], v[88:89] op_sel:[1,0] op_sel_hi:[1,1]
	v_pk_fma_f32 v[86:87], v[170:171], v[86:87], v[154:155]
	v_pk_fma_f32 v[88:89], v[172:173], v[88:89], v[156:157]
	v_pk_mul_f32 v[82:83], v[224:225], v[82:83] op_sel:[1,0] op_sel_hi:[1,1]
	v_pk_mul_f32 v[84:85], v[224:225], v[84:85] op_sel:[1,0] op_sel_hi:[1,1]
	v_pk_fma_f32 v[82:83], v[218:219], v[82:83], v[158:159]
	v_pk_fma_f32 v[84:85], v[220:221], v[84:85], v[160:161]
	v_add_u32_e32 v45, 0x280000, v44
	global_load_dwordx4 v[146:149], v45, s[64:65] offset:0
	global_load_dwordx4 v[150:153], v45, s[64:65] offset:64
	global_load_dwordx4 v[154:157], v45, s[64:65] offset:512
	global_load_dwordx4 v[158:161], v45, s[64:65] offset:576
	v_add_u32_e32 v62, 0x3000, v36
	v_add_u32_e32 v65, 0x60000, v40
	global_store_dwordx4 v62, v[94:97], s[98:99] offset:0
	v_cvt_pk_bf16_f32 v240, v94, v95
	v_cvt_pk_bf16_f32 v241, v96, v97
	v_mul_f32_e32 v230, v95, v95
	v_mul_f32_e32 v231, v97, v97
; __device__ __forceinline__ unsigned cvt_pk_bf16(float lo, float hi) { unsigned r; asm volatile("s_nop 0\n\tv_cvt_pk_bf16_f32 %0, %1, %2" : "=v"(r) : "v"(lo), "v"(hi)); return r; }
; __device__ __forceinline__ f32x4 sig4(const f32x4 v) { return (f32x4){sigmoidf_(v[0]), sigmoidf_(v[1]), sigmoidf_(v[2]), sigmoidf_(v[3])}; }
;     __device__ __forceinline__ void operator()(const typename AccT<I8>::type (&acc)[2][2][4][2], const Unit& u, int wr, int wc, int fr, int fq) const {
;     ...
;         for (int s = 0; s < 8; ++s) { const int ai = s >> 2, m = s & 3; const int r = row0 + ai * HALF + m * 16; const size_t off = (size_t)r * 4096 + col0;
;                 if (s + 1 < 8) load_row(nxt, (size_t)(row0 + ((s + 1) >> 2) * HALF + ((s + 1) & 3) * 16) * 4096 + col0);
;                 const float rs = rsv[s];
;                 float ss = 0.f, mx = 0.f;
; #pragma unroll
;                 for (int bj = 0; bj < 2; ++bj)
; #pragma unroll
;                     for (int n = 0; n < 2; ++n) { const size_t o = off + bj * HALF + n * 16; const f32x4 b = cur.b[bj][n]; f32x4 v;
;                         if constexpr (I8) v = __builtin_convertvector(acc[ai][bj][m][n], f32x4) * rs * sv[bj][n]; else v = acc[ai][bj][m][n];
;                         if (MODE == 1) { const u32x2 pw = cur.pw[bj][n]; const f32x4 pp = (f32x4){bf_lo(pw.x), bf_hi(pw.x), bf_lo(pw.y), bf_hi(pw.y)}; v = sig4(I8 ? v : v * rs) * pp; }
;                         const f32x4 x = b + v; *(f32x4*)(out + o) = x;
;                         if (MODE == 0 && XB) { u32x2 w; w.x = cvt_pk_bf16(x[0], x[1]); w.y = cvt_pk_bf16(x[2], x[3]); *(u32x2*)(XB + o) = w; ss += (x[0] * x[0] + x[1] * x[1]) + (x[2] * x[2] + x[3] * x[3]);
;                             if (RM) mx = fmaxf(fmaxf(mx, fmaxf(fabsf(x[0]), fabsf(x[1]))), fmaxf(fabsf(x[2]), fabsf(x[3]))); } }
;                 if (MODE == 0 && XB) { ss += __shfl_xor(ss, 16); ss += __shfl_xor(ss, 32); if (fq == 0) unsafeAtomicAdd(SS + r, ss);
;                     if (RM) { mx = fmaxf(mx, __shfl_xor(mx, 16)); mx = fmaxf(mx, __shfl_xor(mx, 32)); if (fq == 0) atomicMax(RM + r, __builtin_bit_cast(unsigned, mx)); } }
;                 cur = nxt; }
	v_fmac_f32_e32 v230, v94, v94
	v_fmac_f32_e32 v231, v96, v96
	v_add_f32_e32 v63, v230, v231
	v_max3_f32 v64, |v94|, |v95|, 0
	v_max3_f32 v64, |v96|, |v97|, v64
	global_store_dwordx4 v62, v[90:93], s[98:99] offset:1024
	v_cvt_pk_bf16_f32 v242, v90, v91
	v_cvt_pk_bf16_f32 v243, v92, v93
	v_mul_f32_e32 v230, v91, v91
	v_mul_f32_e32 v231, v93, v93
	v_fmac_f32_e32 v230, v90, v90
	v_fmac_f32_e32 v231, v92, v92
	v_permlane16_swap_b32_e32 v240, v242
	v_permlane16_swap_b32_e32 v241, v243
	v_add_f32_e32 v230, v230, v231
	v_add_f32_e32 v63, v63, v230
	v_max3_f32 v64, |v90|, |v91|, v64
	v_max3_f32 v64, |v92|, |v93|, v64
	global_store_dwordx4 v65, v[240:243], s[68:69] offset:0
	global_store_dwordx4 v62, v[86:89], s[98:99] offset:2048
	v_cvt_pk_bf16_f32 v244, v86, v87
	v_cvt_pk_bf16_f32 v245, v88, v89
	v_mul_f32_e32 v230, v87, v87
	v_mul_f32_e32 v231, v89, v89
	v_fmac_f32_e32 v230, v86, v86
	v_fmac_f32_e32 v231, v88, v88
	v_add_f32_e32 v230, v230, v231
	v_add_f32_e32 v63, v63, v230
	v_max3_f32 v64, |v86|, |v87|, v64
	v_max3_f32 v64, |v88|, |v89|, v64
	global_store_dwordx4 v62, v[82:85], s[98:99] offset:3072
	v_cvt_pk_bf16_f32 v246, v82, v83
	v_cvt_pk_bf16_f32 v247, v84, v85
	v_mul_f32_e32 v230, v83, v83
	v_mul_f32_e32 v231, v85, v85
	v_fmac_f32_e32 v230, v82, v82
	v_fmac_f32_e32 v231, v84, v84
	v_permlane16_swap_b32_e32 v244, v246
	v_permlane16_swap_b32_e32 v245, v247
	v_add_f32_e32 v230, v230, v231
	v_add_f32_e32 v63, v63, v230
	v_max3_f32 v64, |v82|, |v83|, v64
	v_max3_f32 v64, |v84|, |v85|, v64
	global_store_dwordx4 v65, v[244:247], s[68:69] offset:256
	ds_bpermute_b32 v238, v42, v63
	ds_bpermute_b32 v239, v42, v64
	s_waitcnt lgkmcnt(0)
	v_add_f32_e32 v63, v63, v238
	v_max_f32_e32 v64, v64, v239
	ds_bpermute_b32 v238, v43, v63
	ds_bpermute_b32 v239, v43, v64
	s_waitcnt lgkmcnt(0)
	v_add_f32_e32 v63, v63, v238
	v_max_f32_e32 v64, v64, v239
	s_mov_b64 exec, s[6:7]
	global_atomic_add_f32 v41, v63, s[10:11] offset:192
	global_atomic_umax v41, v64, s[12:13] offset:192
	s_mov_b64 exec, -1
	s_waitcnt vmcnt(32)
	v_pk_mul_f32 v[78:79], v[226:227], v[78:79] op_sel:[0,0] op_sel_hi:[0,1]
	v_pk_mul_f32 v[80:81], v[226:227], v[80:81] op_sel:[0,0] op_sel_hi:[0,1]
	v_pk_fma_f32 v[78:79], v[162:163], v[78:79], v[186:187]
	v_pk_fma_f32 v[80:81], v[164:165], v[80:81], v[188:189]
	v_pk_mul_f32 v[74:75], v[226:227], v[74:75] op_sel:[0,0] op_sel_hi:[0,1]
	v_pk_mul_f32 v[76:77], v[226:227], v[76:77] op_sel:[0,0] op_sel_hi:[0,1]
	v_pk_fma_f32 v[74:75], v[166:167], v[74:75], v[190:191]
	v_pk_fma_f32 v[76:77], v[168:169], v[76:77], v[192:193]
	v_pk_mul_f32 v[70:71], v[226:227], v[70:71] op_sel:[0,0] op_sel_hi:[0,1]
	v_pk_mul_f32 v[72:73], v[226:227], v[72:73] op_sel:[0,0] op_sel_hi:[0,1]
	v_pk_fma_f32 v[70:71], v[170:171], v[70:71], v[194:195]
	v_pk_fma_f32 v[72:73], v[172:173], v[72:73], v[196:197]
	v_pk_mul_f32 v[66:67], v[226:227], v[66:67] op_sel:[0,0] op_sel_hi:[0,1]
	v_pk_mul_f32 v[68:69], v[226:227], v[68:69] op_sel:[0,0] op_sel_hi:[0,1]
	v_pk_fma_f32 v[66:67], v[218:219], v[66:67], v[198:199]
	v_pk_fma_f32 v[68:69], v[220:221], v[68:69], v[200:201]
	v_add_u32_e32 v45, 0x2c0000, v44
	global_load_dwordx4 v[186:189], v45, s[64:65] offset:0
	global_load_dwordx4 v[190:193], v45, s[64:65] offset:64
	global_load_dwordx4 v[194:197], v45, s[64:65] offset:512
	global_load_dwordx4 v[198:201], v45, s[64:65] offset:576
	v_add_u32_e32 v62, 0x4000, v36
	v_add_u32_e32 v65, 0x100000, v40
	global_store_dwordx4 v62, v[78:81], s[98:99] offset:0
	v_cvt_pk_bf16_f32 v240, v78, v79
	v_cvt_pk_bf16_f32 v241, v80, v81
	v_mul_f32_e32 v230, v79, v79
	v_mul_f32_e32 v231, v81, v81
	v_fmac_f32_e32 v230, v78, v78
	v_fmac_f32_e32 v231, v80, v80
	v_add_f32_e32 v63, v230, v231
	v_max3_f32 v64, |v78|, |v79|, 0
	v_max3_f32 v64, |v80|, |v81|, v64
	global_store_dwordx4 v62, v[74:77], s[98:99] offset:1024
	v_cvt_pk_bf16_f32 v242, v74, v75
	v_cvt_pk_bf16_f32 v243, v76, v77
	v_mul_f32_e32 v230, v75, v75
	v_mul_f32_e32 v231, v77, v77
	v_fmac_f32_e32 v230, v74, v74
	v_fmac_f32_e32 v231, v76, v76
	v_permlane16_swap_b32_e32 v240, v242
	v_permlane16_swap_b32_e32 v241, v243
	v_add_f32_e32 v230, v230, v231
	v_add_f32_e32 v63, v63, v230
	v_max3_f32 v64, |v74|, |v75|, v64
	v_max3_f32 v64, |v76|, |v77|, v64
	global_store_dwordx4 v65, v[240:243], s[68:69] offset:0
	global_store_dwordx4 v62, v[70:73], s[98:99] offset:2048
	v_cvt_pk_bf16_f32 v244, v70, v71
	v_cvt_pk_bf16_f32 v245, v72, v73
	v_mul_f32_e32 v230, v71, v71
	v_mul_f32_e32 v231, v73, v73
	v_fmac_f32_e32 v230, v70, v70
	v_fmac_f32_e32 v231, v72, v72
	v_add_f32_e32 v230, v230, v231
	v_add_f32_e32 v63, v63, v230
	v_max3_f32 v64, |v70|, |v71|, v64
	v_max3_f32 v64, |v72|, |v73|, v64
	global_store_dwordx4 v62, v[66:69], s[98:99] offset:3072
	v_cvt_pk_bf16_f32 v246, v66, v67
	v_cvt_pk_bf16_f32 v247, v68, v69
	v_mul_f32_e32 v230, v67, v67
	v_mul_f32_e32 v231, v69, v69
	v_fmac_f32_e32 v230, v66, v66
	v_fmac_f32_e32 v231, v68, v68
	v_permlane16_swap_b32_e32 v244, v246
	v_permlane16_swap_b32_e32 v245, v247
	v_add_f32_e32 v230, v230, v231
	v_add_f32_e32 v63, v63, v230
	v_max3_f32 v64, |v66|, |v67|, v64
	v_max3_f32 v64, |v68|, |v69|, v64
	global_store_dwordx4 v65, v[244:247], s[68:69] offset:256
	ds_bpermute_b32 v238, v42, v63
	ds_bpermute_b32 v239, v42, v64
	s_waitcnt lgkmcnt(0)
	v_add_f32_e32 v63, v63, v238
	v_max_f32_e32 v64, v64, v239
	ds_bpermute_b32 v238, v43, v63
	ds_bpermute_b32 v239, v43, v64
	s_waitcnt lgkmcnt(0)
	v_add_f32_e32 v63, v63, v238
	v_max_f32_e32 v64, v64, v239
	s_mov_b64 exec, s[6:7]
	global_atomic_add_f32 v41, v63, s[10:11] offset:512
	global_atomic_umax v41, v64, s[12:13] offset:512
	s_mov_b64 exec, -1
	s_waitcnt vmcnt(32)
; __device__ __forceinline__ unsigned cvt_pk_bf16(float lo, float hi) { unsigned r; asm volatile("s_nop 0\n\tv_cvt_pk_bf16_f32 %0, %1, %2" : "=v"(r) : "v"(lo), "v"(hi)); return r; }
; __device__ __forceinline__ f32x4 sig4(const f32x4 v) { return (f32x4){sigmoidf_(v[0]), sigmoidf_(v[1]), sigmoidf_(v[2]), sigmoidf_(v[3])}; }
;     __device__ __forceinline__ void operator()(const typename AccT<I8>::type (&acc)[2][2][4][2], const Unit& u, int wr, int wc, int fr, int fq) const {
;     ...
;         for (int s = 0; s < 8; ++s) { const int ai = s >> 2, m = s & 3; const int r = row0 + ai * HALF + m * 16; const size_t off = (size_t)r * 4096 + col0;
;                 if (s + 1 < 8) load_row(nxt, (size_t)(row0 + ((s + 1) >> 2) * HALF + ((s + 1) & 3) * 16) * 4096 + col0);
;                 const float rs = rsv[s];
;                 float ss = 0.f, mx = 0.f;
; #pragma unroll
;                 for (int bj = 0; bj < 2; ++bj)
; #pragma unroll
;                     for (int n = 0; n < 2; ++n) { const size_t o = off + bj * HALF + n * 16; const f32x4 b = cur.b[bj][n]; f32x4 v;
;                         if constexpr (I8) v = __builtin_convertvector(acc[ai][bj][m][n], f32x4) * rs * sv[bj][n]; else v = acc[ai][bj][m][n];
;                         if (MODE == 1) { const u32x2 pw = cur.pw[bj][n]; const f32x4 pp = (f32x4){bf_lo(pw.x), bf_hi(pw.x), bf_lo(pw.y), bf_hi(pw.y)}; v = sig4(I8 ? v : v * rs) * pp; }
;                         const f32x4 x = b + v; *(f32x4*)(out + o) = x;
;                         if (MODE == 0 && XB) { u32x2 w; w.x = cvt_pk_bf16(x[0], x[1]); w.y = cvt_pk_bf16(x[2], x[3]); *(u32x2*)(XB + o) = w; ss += (x[0] * x[0] + x[1] * x[1]) + (x[2] * x[2] + x[3] * x[3]);
;                             if (RM) mx = fmaxf(fmaxf(mx, fmaxf(fabsf(x[0]), fabsf(x[1]))), fmaxf(fabsf(x[2]), fabsf(x[3]))); } }
;                 if (MODE == 0 && XB) { ss += __shfl_xor(ss, 16); ss += __shfl_xor(ss, 32); if (fq == 0) unsafeAtomicAdd(SS + r, ss);
;                     if (RM) { mx = fmaxf(mx, __shfl_xor(mx, 16)); mx = fmaxf(mx, __shfl_xor(mx, 32)); if (fq == 0) atomicMax(RM + r, __builtin_bit_cast(unsigned, mx)); } }
;                 cur = nxt; }
	v_pk_mul_f32 v[58:59], v[226:227], v[58:59] op_sel:[1,0] op_sel_hi:[1,1]
	v_pk_mul_f32 v[60:61], v[226:227], v[60:61] op_sel:[1,0] op_sel_hi:[1,1]
	v_pk_fma_f32 v[58:59], v[162:163], v[58:59], v[202:203]
	v_pk_fma_f32 v[60:61], v[164:165], v[60:61], v[204:205]
	v_pk_mul_f32 v[54:55], v[226:227], v[54:55] op_sel:[1,0] op_sel_hi:[1,1]
	v_pk_mul_f32 v[56:57], v[226:227], v[56:57] op_sel:[1,0] op_sel_hi:[1,1]
	v_pk_fma_f32 v[54:55], v[166:167], v[54:55], v[206:207]
	v_pk_fma_f32 v[56:57], v[168:169], v[56:57], v[208:209]
	v_pk_mul_f32 v[50:51], v[226:227], v[50:51] op_sel:[1,0] op_sel_hi:[1,1]
	v_pk_mul_f32 v[52:53], v[226:227], v[52:53] op_sel:[1,0] op_sel_hi:[1,1]
	v_pk_fma_f32 v[50:51], v[170:171], v[50:51], v[210:211]
	v_pk_fma_f32 v[52:53], v[172:173], v[52:53], v[212:213]
	v_pk_mul_f32 v[46:47], v[226:227], v[46:47] op_sel:[1,0] op_sel_hi:[1,1]
	v_pk_mul_f32 v[48:49], v[226:227], v[48:49] op_sel:[1,0] op_sel_hi:[1,1]
	v_pk_fma_f32 v[46:47], v[218:219], v[46:47], v[214:215]
	v_pk_fma_f32 v[48:49], v[220:221], v[48:49], v[216:217]
	v_add_u32_e32 v62, 0x5000, v36
	v_add_u32_e32 v65, 0x120000, v40
	global_store_dwordx4 v62, v[58:61], s[98:99] offset:0
	v_cvt_pk_bf16_f32 v240, v58, v59
	v_cvt_pk_bf16_f32 v241, v60, v61
	v_mul_f32_e32 v230, v59, v59
	v_mul_f32_e32 v231, v61, v61
	v_fmac_f32_e32 v230, v58, v58
	v_fmac_f32_e32 v231, v60, v60
	v_add_f32_e32 v63, v230, v231
	v_max3_f32 v64, |v58|, |v59|, 0
	v_max3_f32 v64, |v60|, |v61|, v64
	global_store_dwordx4 v62, v[54:57], s[98:99] offset:1024
	v_cvt_pk_bf16_f32 v242, v54, v55
	v_cvt_pk_bf16_f32 v243, v56, v57
	v_mul_f32_e32 v230, v55, v55
	v_mul_f32_e32 v231, v57, v57
	v_fmac_f32_e32 v230, v54, v54
	v_fmac_f32_e32 v231, v56, v56
	v_permlane16_swap_b32_e32 v240, v242
	v_permlane16_swap_b32_e32 v241, v243
	v_add_f32_e32 v230, v230, v231
	v_add_f32_e32 v63, v63, v230
	v_max3_f32 v64, |v54|, |v55|, v64
	v_max3_f32 v64, |v56|, |v57|, v64
	global_store_dwordx4 v65, v[240:243], s[68:69] offset:0
	global_store_dwordx4 v62, v[50:53], s[98:99] offset:2048
	v_cvt_pk_bf16_f32 v244, v50, v51
	v_cvt_pk_bf16_f32 v245, v52, v53
	v_mul_f32_e32 v230, v51, v51
	v_mul_f32_e32 v231, v53, v53
	v_fmac_f32_e32 v230, v50, v50
	v_fmac_f32_e32 v231, v52, v52
	v_add_f32_e32 v230, v230, v231
	v_add_f32_e32 v63, v63, v230
	v_max3_f32 v64, |v50|, |v51|, v64
	v_max3_f32 v64, |v52|, |v53|, v64
	global_store_dwordx4 v62, v[46:49], s[98:99] offset:3072
	v_cvt_pk_bf16_f32 v246, v46, v47
	v_cvt_pk_bf16_f32 v247, v48, v49
	v_mul_f32_e32 v230, v47, v47
	v_mul_f32_e32 v231, v49, v49
	v_fmac_f32_e32 v230, v46, v46
	v_fmac_f32_e32 v231, v48, v48
	v_permlane16_swap_b32_e32 v244, v246
	v_permlane16_swap_b32_e32 v245, v247
	v_add_f32_e32 v230, v230, v231
	v_add_f32_e32 v63, v63, v230
	v_max3_f32 v64, |v46|, |v47|, v64
	v_max3_f32 v64, |v48|, |v49|, v64
	global_store_dwordx4 v65, v[244:247], s[68:69] offset:256
	ds_bpermute_b32 v238, v42, v63
	ds_bpermute_b32 v239, v42, v64
	s_waitcnt lgkmcnt(0)
	v_add_f32_e32 v63, v63, v238
	v_max_f32_e32 v64, v64, v239
	ds_bpermute_b32 v238, v43, v63
	ds_bpermute_b32 v239, v43, v64
	s_waitcnt lgkmcnt(0)
	v_add_f32_e32 v63, v63, v238
	v_max_f32_e32 v64, v64, v239
	s_mov_b64 exec, s[6:7]
	global_atomic_add_f32 v41, v63, s[10:11] offset:576
	global_atomic_umax v41, v64, s[12:13] offset:576
	s_mov_b64 exec, -1
	s_waitcnt vmcnt(28)
	v_pk_mul_f32 v[30:31], v[228:229], v[30:31] op_sel:[0,0] op_sel_hi:[0,1]
	v_pk_mul_f32 v[32:33], v[228:229], v[32:33] op_sel:[0,0] op_sel_hi:[0,1]
	v_pk_fma_f32 v[30:31], v[162:163], v[30:31], v[146:147]
	v_pk_fma_f32 v[32:33], v[164:165], v[32:33], v[148:149]
	v_pk_mul_f32 v[26:27], v[228:229], v[26:27] op_sel:[0,0] op_sel_hi:[0,1]
	v_pk_mul_f32 v[28:29], v[228:229], v[28:29] op_sel:[0,0] op_sel_hi:[0,1]
	v_pk_fma_f32 v[26:27], v[166:167], v[26:27], v[150:151]
	v_pk_fma_f32 v[28:29], v[168:169], v[28:29], v[152:153]
	v_pk_mul_f32 v[22:23], v[228:229], v[22:23] op_sel:[0,0] op_sel_hi:[0,1]
	v_pk_mul_f32 v[24:25], v[228:229], v[24:25] op_sel:[0,0] op_sel_hi:[0,1]
	v_pk_fma_f32 v[22:23], v[170:171], v[22:23], v[154:155]
	v_pk_fma_f32 v[24:25], v[172:173], v[24:25], v[156:157]
	v_pk_mul_f32 v[18:19], v[228:229], v[18:19] op_sel:[0,0] op_sel_hi:[0,1]
	v_pk_mul_f32 v[20:21], v[228:229], v[20:21] op_sel:[0,0] op_sel_hi:[0,1]
	v_pk_fma_f32 v[18:19], v[218:219], v[18:19], v[158:159]
	v_pk_fma_f32 v[20:21], v[220:221], v[20:21], v[160:161]
	v_add_u32_e32 v62, 0x6000, v36
	v_add_u32_e32 v65, 0x140000, v40
	global_store_dwordx4 v62, v[30:33], s[98:99] offset:0
	v_cvt_pk_bf16_f32 v240, v30, v31
	v_cvt_pk_bf16_f32 v241, v32, v33
	v_mul_f32_e32 v230, v31, v31
	v_mul_f32_e32 v231, v33, v33
	v_fmac_f32_e32 v230, v30, v30
	v_fmac_f32_e32 v231, v32, v32
	v_add_f32_e32 v63, v230, v231
	v_max3_f32 v64, |v30|, |v31|, 0
	v_max3_f32 v64, |v32|, |v33|, v64
	global_store_dwordx4 v62, v[26:29], s[98:99] offset:1024
	v_cvt_pk_bf16_f32 v242, v26, v27
	v_cvt_pk_bf16_f32 v243, v28, v29
	v_mul_f32_e32 v230, v27, v27
	v_mul_f32_e32 v231, v29, v29
	v_fmac_f32_e32 v230, v26, v26
	v_fmac_f32_e32 v231, v28, v28
	v_permlane16_swap_b32_e32 v240, v242
	v_permlane16_swap_b32_e32 v241, v243
	v_add_f32_e32 v230, v230, v231
	v_add_f32_e32 v63, v63, v230
	v_max3_f32 v64, |v26|, |v27|, v64
	v_max3_f32 v64, |v28|, |v29|, v64
	global_store_dwordx4 v65, v[240:243], s[68:69] offset:0
	global_store_dwordx4 v62, v[22:25], s[98:99] offset:2048
	v_cvt_pk_bf16_f32 v244, v22, v23
	v_cvt_pk_bf16_f32 v245, v24, v25
	v_mul_f32_e32 v230, v23, v23
	v_mul_f32_e32 v231, v25, v25
	v_fmac_f32_e32 v230, v22, v22
	v_fmac_f32_e32 v231, v24, v24
	v_add_f32_e32 v230, v230, v231
	v_add_f32_e32 v63, v63, v230
	v_max3_f32 v64, |v22|, |v23|, v64
	v_max3_f32 v64, |v24|, |v25|, v64
	global_store_dwordx4 v62, v[18:21], s[98:99] offset:3072
	v_cvt_pk_bf16_f32 v246, v18, v19
	v_cvt_pk_bf16_f32 v247, v20, v21
	v_mul_f32_e32 v230, v19, v19
	v_mul_f32_e32 v231, v21, v21
	v_fmac_f32_e32 v230, v18, v18
	v_fmac_f32_e32 v231, v20, v20
	v_permlane16_swap_b32_e32 v244, v246
	v_permlane16_swap_b32_e32 v245, v247
	v_add_f32_e32 v230, v230, v231
	v_add_f32_e32 v63, v63, v230
	v_max3_f32 v64, |v18|, |v19|, v64
	v_max3_f32 v64, |v20|, |v21|, v64
	global_store_dwordx4 v65, v[244:247], s[68:69] offset:256
	ds_bpermute_b32 v238, v42, v63
	ds_bpermute_b32 v239, v42, v64
	s_waitcnt lgkmcnt(0)
; __device__ __forceinline__ unsigned cvt_pk_bf16(float lo, float hi) { unsigned r; asm volatile("s_nop 0\n\tv_cvt_pk_bf16_f32 %0, %1, %2" : "=v"(r) : "v"(lo), "v"(hi)); return r; }
; __device__ __forceinline__ f32x4 sig4(const f32x4 v) { return (f32x4){sigmoidf_(v[0]), sigmoidf_(v[1]), sigmoidf_(v[2]), sigmoidf_(v[3])}; }
;     __device__ __forceinline__ void operator()(const typename AccT<I8>::type (&acc)[2][2][4][2], const Unit& u, int wr, int wc, int fr, int fq) const {
;     ...
;         for (int s = 0; s < 8; ++s) { const int ai = s >> 2, m = s & 3; const int r = row0 + ai * HALF + m * 16; const size_t off = (size_t)r * 4096 + col0;
;                 if (s + 1 < 8) load_row(nxt, (size_t)(row0 + ((s + 1) >> 2) * HALF + ((s + 1) & 3) * 16) * 4096 + col0);
;                 const float rs = rsv[s];
;                 float ss = 0.f, mx = 0.f;
; #pragma unroll
;                 for (int bj = 0; bj < 2; ++bj)
; #pragma unroll
;                     for (int n = 0; n < 2; ++n) { const size_t o = off + bj * HALF + n * 16; const f32x4 b = cur.b[bj][n]; f32x4 v;
;                         if constexpr (I8) v = __builtin_convertvector(acc[ai][bj][m][n], f32x4) * rs * sv[bj][n]; else v = acc[ai][bj][m][n];
;                         if (MODE == 1) { const u32x2 pw = cur.pw[bj][n]; const f32x4 pp = (f32x4){bf_lo(pw.x), bf_hi(pw.x), bf_lo(pw.y), bf_hi(pw.y)}; v = sig4(I8 ? v : v * rs) * pp; }
;                         const f32x4 x = b + v; *(f32x4*)(out + o) = x;
;                         if (MODE == 0 && XB) { u32x2 w; w.x = cvt_pk_bf16(x[0], x[1]); w.y = cvt_pk_bf16(x[2], x[3]); *(u32x2*)(XB + o) = w; ss += (x[0] * x[0] + x[1] * x[1]) + (x[2] * x[2] + x[3] * x[3]);
;                             if (RM) mx = fmaxf(fmaxf(mx, fmaxf(fabsf(x[0]), fabsf(x[1]))), fmaxf(fabsf(x[2]), fabsf(x[3]))); } }
;                 if (MODE == 0 && XB) { ss += __shfl_xor(ss, 16); ss += __shfl_xor(ss, 32); if (fq == 0) unsafeAtomicAdd(SS + r, ss);
;                     if (RM) { mx = fmaxf(mx, __shfl_xor(mx, 16)); mx = fmaxf(mx, __shfl_xor(mx, 32)); if (fq == 0) atomicMax(RM + r, __builtin_bit_cast(unsigned, mx)); } }
;                 cur = nxt; }
	v_add_f32_e32 v63, v63, v238
	v_max_f32_e32 v64, v64, v239
	ds_bpermute_b32 v238, v43, v63
	ds_bpermute_b32 v239, v43, v64
	s_waitcnt lgkmcnt(0)
	v_add_f32_e32 v63, v63, v238
	v_max_f32_e32 v64, v64, v239
	s_mov_b64 exec, s[6:7]
	global_atomic_add_f32 v41, v63, s[10:11] offset:640
	global_atomic_umax v41, v64, s[12:13] offset:640
	s_mov_b64 exec, -1
	s_waitcnt vmcnt(24)
	v_pk_mul_f32 v[14:15], v[228:229], v[14:15] op_sel:[1,0] op_sel_hi:[1,1]
	v_pk_mul_f32 v[16:17], v[228:229], v[16:17] op_sel:[1,0] op_sel_hi:[1,1]
	v_pk_fma_f32 v[14:15], v[162:163], v[14:15], v[186:187]
	v_pk_fma_f32 v[16:17], v[164:165], v[16:17], v[188:189]
	v_pk_mul_f32 v[10:11], v[228:229], v[10:11] op_sel:[1,0] op_sel_hi:[1,1]
	v_pk_mul_f32 v[12:13], v[228:229], v[12:13] op_sel:[1,0] op_sel_hi:[1,1]
	v_pk_fma_f32 v[10:11], v[166:167], v[10:11], v[190:191]
	v_pk_fma_f32 v[12:13], v[168:169], v[12:13], v[192:193]
	v_pk_mul_f32 v[6:7], v[228:229], v[6:7] op_sel:[1,0] op_sel_hi:[1,1]
	v_pk_mul_f32 v[8:9], v[228:229], v[8:9] op_sel:[1,0] op_sel_hi:[1,1]
	v_pk_fma_f32 v[6:7], v[170:171], v[6:7], v[194:195]
	v_pk_fma_f32 v[8:9], v[172:173], v[8:9], v[196:197]
	v_pk_mul_f32 v[2:3], v[228:229], v[2:3] op_sel:[1,0] op_sel_hi:[1,1]
	v_pk_mul_f32 v[4:5], v[228:229], v[4:5] op_sel:[1,0] op_sel_hi:[1,1]
	v_pk_fma_f32 v[2:3], v[218:219], v[2:3], v[198:199]
	v_pk_fma_f32 v[4:5], v[220:221], v[4:5], v[200:201]
	v_add_u32_e32 v62, 0x7000, v36
	v_add_u32_e32 v65, 0x160000, v40
	global_store_dwordx4 v62, v[14:17], s[98:99] offset:0
	v_cvt_pk_bf16_f32 v240, v14, v15
	v_cvt_pk_bf16_f32 v241, v16, v17
	v_mul_f32_e32 v230, v15, v15
	v_mul_f32_e32 v231, v17, v17
	v_fmac_f32_e32 v230, v14, v14
	v_fmac_f32_e32 v231, v16, v16
	v_add_f32_e32 v63, v230, v231
	v_max3_f32 v64, |v14|, |v15|, 0
	v_max3_f32 v64, |v16|, |v17|, v64
	global_store_dwordx4 v62, v[10:13], s[98:99] offset:1024
	v_cvt_pk_bf16_f32 v242, v10, v11
	v_cvt_pk_bf16_f32 v243, v12, v13
	v_mul_f32_e32 v230, v11, v11
	v_mul_f32_e32 v231, v13, v13
	v_fmac_f32_e32 v230, v10, v10
	v_fmac_f32_e32 v231, v12, v12
	v_permlane16_swap_b32_e32 v240, v242
	v_permlane16_swap_b32_e32 v241, v243
	v_add_f32_e32 v230, v230, v231
	v_add_f32_e32 v63, v63, v230
	v_max3_f32 v64, |v10|, |v11|, v64
	v_max3_f32 v64, |v12|, |v13|, v64
	global_store_dwordx4 v65, v[240:243], s[68:69] offset:0
	global_store_dwordx4 v62, v[6:9], s[98:99] offset:2048
	v_cvt_pk_bf16_f32 v244, v6, v7
	v_cvt_pk_bf16_f32 v245, v8, v9
	v_mul_f32_e32 v230, v7, v7
	v_mul_f32_e32 v231, v9, v9
	v_fmac_f32_e32 v230, v6, v6
	v_fmac_f32_e32 v231, v8, v8
	v_add_f32_e32 v230, v230, v231
	v_add_f32_e32 v63, v63, v230
	v_max3_f32 v64, |v6|, |v7|, v64
	v_max3_f32 v64, |v8|, |v9|, v64
	global_store_dwordx4 v62, v[2:5], s[98:99] offset:3072
	v_cvt_pk_bf16_f32 v246, v2, v3
	v_cvt_pk_bf16_f32 v247, v4, v5
	v_mul_f32_e32 v230, v3, v3
	v_mul_f32_e32 v231, v5, v5
	v_fmac_f32_e32 v230, v2, v2
	v_fmac_f32_e32 v231, v4, v4
	v_permlane16_swap_b32_e32 v244, v246
	v_permlane16_swap_b32_e32 v245, v247
	v_add_f32_e32 v230, v230, v231
	v_add_f32_e32 v63, v63, v230
	v_max3_f32 v64, |v2|, |v3|, v64
	v_max3_f32 v64, |v4|, |v5|, v64
	global_store_dwordx4 v65, v[244:247], s[68:69] offset:256
	ds_bpermute_b32 v238, v42, v63
	ds_bpermute_b32 v239, v42, v64
	s_waitcnt lgkmcnt(0)
	v_add_f32_e32 v63, v63, v238
	v_max_f32_e32 v64, v64, v239
	ds_bpermute_b32 v238, v43, v63
	ds_bpermute_b32 v239, v43, v64
	s_waitcnt lgkmcnt(0)
	v_add_f32_e32 v63, v63, v238
	v_max_f32_e32 v64, v64, v239
	s_mov_b64 exec, s[6:7]
	global_atomic_add_f32 v41, v63, s[10:11] offset:704
	global_atomic_umax v41, v64, s[12:13] offset:704
	s_mov_b64 exec, -1
	v_readlane_b32 s68, v254, 8
	v_readlane_b32 s69, v254, 9
	v_readlane_b32 s70, v254, 10
	v_readlane_b32 s71, v254, 11
	v_readlane_b32 s72, v254, 12
	v_readlane_b32 s73, v254, 13
	v_readlane_b32 s74, v254, 14
	v_readlane_b32 s75, v254, 15

;     __device__ __forceinline__ void operator()(const typename AccT<I8>::type (&acc)[2][2][4][2], const Unit& u, int wr, int wc, int fr, int fq) const {
;         const int row0 = u.pm * BM + wr * 64 + fr, col0 = u.pn * BM + wc * 32 + 4 * fq;
;         f32x4 sv[2][2];
;         if (I8) {
; #pragma unroll
;             for (int bj = 0; bj < 2; ++bj)
; #pragma unroll
;                 for (int n = 0; n < 2; ++n) sv[bj][n] = *(const f32x4*)(swc + col0 + bj * HALF + n * 16);
;         }
;         float rsv[8];
; #pragma unroll
;         for (int s = 0; s < 8; ++s) { const int r = row0 + (s >> 2) * HALF + (s & 3) * 16; float rs = 1.f; if (MODE == 1) rs = __builtin_amdgcn_rsqf(rstd[r] * (1.0f / 4096.0f) + 1e-6f); if (I8) rs *= sxr[r]; rsv[s] = rs; }
;         RowIn cur, nxt;
;         load_row(cur, (size_t)row0 * 4096 + col0);
; #pragma unroll
;         for (int s = 0; s < 8; ++s) { const int ai = s >> 2, m = s & 3; const int r = row0 + ai * HALF + m * 16; const size_t off = (size_t)r * 4096 + col0;
;                 if (s + 1 < 8) load_row(nxt, (size_t)(row0 + ((s + 1) >> 2) * HALF + ((s + 1) & 3) * 16) * 4096 + col0);
;                 const float rs = rsv[s];
;                 float ss = 0.f, mx = 0.f;
; #pragma unroll
;                 for (int bj = 0; bj < 2; ++bj)
; #pragma unroll
;                     for (int n = 0; n < 2; ++n) { const size_t o = off + bj * HALF + n * 16; const f32x4 b = cur.b[bj][n]; f32x4 v;
;                         if constexpr (I8) v = __builtin_convertvector(acc[ai][bj][m][n], f32x4) * rs * sv[bj][n]; else v = acc[ai][bj][m][n];
;                         if (MODE == 1) { const u32x2 pw = cur.pw[bj][n]; const f32x4 pp = (f32x4){bf_lo(pw.x), bf_hi(pw.x), bf_lo(pw.y), bf_hi(pw.y)}; v = sig4(I8 ? v : v * rs) * pp; }
;                         const f32x4 x = b + v; *(f32x4*)(out + o) = x;
;                         if (MODE == 0 && XB) { u32x2 w; w.x = cvt_pk_bf16(x[0], x[1]); w.y = cvt_pk_bf16(x[2], x[3]); *(u32x2*)(XB + o) = w; ss += (x[0] * x[0] + x[1] * x[1]) + (x[2] * x[2] + x[3] * x[3]);
;                             if (RM) mx = fmaxf(fmaxf(mx, fmaxf(fabsf(x[0]), fabsf(x[1]))), fmaxf(fabsf(x[2]), fabsf(x[3]))); } }
;                 if (MODE == 0 && XB) { ss += __shfl_xor(ss, 16); ss += __shfl_xor(ss, 32); if (fq == 0) unsafeAtomicAdd(SS + r, ss);
.LBB0_2095:
	s_lshl_b32 s98, s6, 4
	s_add_i32 s98, s98, s2
	s_sub_i32 s99, s98, 888
	s_cmp_lt_u32 s98, 888
	s_cselect_b32 s98, s98, s99
	s_mov_b32 s99, 0x4200000
	s_cselect_b32 s99, 0x3f600000, s99
	s_lshl_b32 s98, s98, 18
	s_add_u32 s98, s98, s99
	s_add_u32 s98, s96, s98
	s_addc_u32 s99, s97, 0
	v_and_b32_e32 v244, 63, v0
	v_lshrrev_b32_e32 v245, 6, v0
	v_lshlrev_b32_e32 v246, 4, v244
	v_lshl_add_u32 v246, v245, 15, v246
	v_lshrrev_b32_e32 v245, 8, v0
	v_and_b32_e32 v247, 15, v0
	v_lshl_add_u32 v245, v245, 6, v247
	v_lshl_add_u32 v248, s6, 8, v245
	v_bfe_u32 v245, v0, 6, 2
	v_bfe_u32 v249, v0, 4, 2
	v_lshlrev_b32_e32 v245, 5, v245
	v_lshl_add_u32 v245, v249, 2, v245
	v_lshl_add_u32 v245, s2, 8, v245
	v_lshlrev_b32_e32 v250, 13, v248
	v_lshl_add_u32 v250, v245, 1, v250
	v_lshlrev_b32_e32 v251, 2, v248
	v_lshlrev_b32_e32 v247, 3, v249
	v_sub_u32_e32 v250, v250, v247
	v_and_b32_e32 v247, 1, v249
	v_lshl_add_u32 v250, v247, 5, v250
	v_lshrrev_b32_e32 v247, 1, v249
	v_lshl_add_u32 v250, v247, 4, v250
	v_xor_b32_e32 v252, 16, v244
	v_xor_b32_e32 v253, 32, v244
	v_lshlrev_b32_e32 v252, 2, v252
	v_lshlrev_b32_e32 v253, 2, v253
	v_cmp_eq_u32_e64 s[6:7], 0, v249
	v_readlane_b32 s52, v254, 40
	v_readlane_b32 s53, v254, 41
	global_load_dwordx4 v[130:133], v246, s[98:99] offset:0
	global_load_dwordx4 v[134:137], v246, s[98:99] offset:1024
	global_load_dwordx4 v[138:141], v246, s[98:99] offset:2048
	global_load_dwordx4 v[142:145], v246, s[98:99] offset:3072
	v_add_u32_e32 v162, 0x1000, v246
	global_load_dwordx4 v[146:149], v162, s[98:99] offset:0
	global_load_dwordx4 v[150:153], v162, s[98:99] offset:1024
	global_load_dwordx4 v[154:157], v162, s[98:99] offset:2048
	global_load_dwordx4 v[158:161], v162, s[98:99] offset:3072
	v_add_u32_e32 v162, 0x2000, v246
	global_load_dwordx4 v[196:199], v162, s[98:99] offset:0
	global_load_dwordx4 v[200:203], v162, s[98:99] offset:1024
	global_load_dwordx4 v[204:207], v162, s[98:99] offset:2048
	global_load_dwordx4 v[208:211], v162, s[98:99] offset:3072
	s_waitcnt vmcnt(8)
	v_pk_add_f32 v[126:127], v[126:127], v[130:131]
	v_pk_add_f32 v[128:129], v[128:129], v[132:133]
	v_pk_add_f32 v[122:123], v[122:123], v[134:135]
	v_pk_add_f32 v[124:125], v[124:125], v[136:137]
	v_pk_add_f32 v[118:119], v[118:119], v[138:139]
	v_pk_add_f32 v[120:121], v[120:121], v[140:141]
	v_pk_add_f32 v[114:115], v[114:115], v[142:143]
	v_pk_add_f32 v[116:117], v[116:117], v[144:145]
	v_add_u32_e32 v162, 0x3000, v246
	global_load_dwordx4 v[130:133], v162, s[98:99] offset:0
	global_load_dwordx4 v[134:137], v162, s[98:99] offset:1024
	global_load_dwordx4 v[138:141], v162, s[98:99] offset:2048
	global_load_dwordx4 v[142:145], v162, s[98:99] offset:3072
	global_store_dwordx4 v246, v[126:129], s[98:99] offset:0
	v_cvt_pk_bf16_f32 v182, v126, v127
	v_cvt_pk_bf16_f32 v183, v128, v129
	v_mul_f32_e32 v166, v127, v127
	v_mul_f32_e32 v167, v129, v129
	v_fmac_f32_e32 v166, v126, v126
	v_fmac_f32_e32 v167, v128, v128
	v_add_f32_e32 v164, v166, v167
	v_max3_f32 v165, |v126|, |v127|, 0
	v_max3_f32 v165, |v128|, |v129|, v165
	global_store_dwordx4 v246, v[122:125], s[98:99] offset:1024
	v_cvt_pk_bf16_f32 v184, v122, v123
	v_cvt_pk_bf16_f32 v185, v124, v125
	v_mul_f32_e32 v166, v123, v123
	v_mul_f32_e32 v167, v125, v125
	v_fmac_f32_e32 v166, v122, v122
	v_fmac_f32_e32 v167, v124, v124
	v_permlane16_swap_b32_e32 v182, v184
	v_permlane16_swap_b32_e32 v183, v185
	v_add_f32_e32 v166, v166, v167
	v_add_f32_e32 v164, v164, v166
	v_max3_f32 v165, |v122|, |v123|, v165
	v_max3_f32 v165, |v124|, |v125|, v165
	global_store_dwordx4 v250, v[182:185], s[52:53] offset:0
	global_store_dwordx4 v246, v[118:121], s[98:99] offset:2048
	v_cvt_pk_bf16_f32 v186, v118, v119
	v_cvt_pk_bf16_f32 v187, v120, v121
	v_mul_f32_e32 v166, v119, v119
	v_mul_f32_e32 v167, v121, v121
	v_fmac_f32_e32 v166, v118, v118
	v_fmac_f32_e32 v167, v120, v120
	v_add_f32_e32 v166, v166, v167
	v_add_f32_e32 v164, v164, v166
	v_max3_f32 v165, |v118|, |v119|, v165
	v_max3_f32 v165, |v120|, |v121|, v165
	global_store_dwordx4 v246, v[114:117], s[98:99] offset:3072
	v_cvt_pk_bf16_f32 v188, v114, v115
	v_cvt_pk_bf16_f32 v189, v116, v117
	v_mul_f32_e32 v166, v115, v115
	v_mul_f32_e32 v167, v117, v117
	v_fmac_f32_e32 v166, v114, v114
	v_fmac_f32_e32 v167, v116, v116
	v_permlane16_swap_b32_e32 v186, v188
	v_permlane16_swap_b32_e32 v187, v189
	v_add_f32_e32 v166, v166, v167
	v_add_f32_e32 v164, v164, v166
	v_max3_f32 v165, |v114|, |v115|, v165
	v_max3_f32 v165, |v116|, |v117|, v165
	global_store_dwordx4 v250, v[186:189], s[52:53] offset:256
	ds_bpermute_b32 v168, v252, v164
	ds_bpermute_b32 v169, v252, v165
	s_waitcnt lgkmcnt(0)
	v_add_f32_e32 v164, v164, v168
	v_max_f32_e32 v165, v165, v169
	ds_bpermute_b32 v168, v253, v164
	ds_bpermute_b32 v169, v253, v165
	s_waitcnt lgkmcnt(0)
	v_add_f32_e32 v164, v164, v168
	v_max_f32_e32 v165, v165, v169
	s_mov_b64 exec, s[6:7]
	global_atomic_add_f32 v251, v164, s[10:11] offset:0
	global_atomic_umax v251, v165, s[12:13] offset:0
	s_mov_b64 exec, -1
	s_waitcnt vmcnt(16)
; __device__ __forceinline__ unsigned cvt_pk_bf16(float lo, float hi) { unsigned r; asm volatile("s_nop 0\n\tv_cvt_pk_bf16_f32 %0, %1, %2" : "=v"(r) : "v"(lo), "v"(hi)); return r; }
; __device__ __forceinline__ f32x4 sig4(const f32x4 v) { return (f32x4){sigmoidf_(v[0]), sigmoidf_(v[1]), sigmoidf_(v[2]), sigmoidf_(v[3])}; }
;     __device__ __forceinline__ void operator()(const typename AccT<I8>::type (&acc)[2][2][4][2], const Unit& u, int wr, int wc, int fr, int fq) const {
;     ...
;         for (int s = 0; s < 8; ++s) { const int ai = s >> 2, m = s & 3; const int r = row0 + ai * HALF + m * 16; const size_t off = (size_t)r * 4096 + col0;
;                 if (s + 1 < 8) load_row(nxt, (size_t)(row0 + ((s + 1) >> 2) * HALF + ((s + 1) & 3) * 16) * 4096 + col0);
;                 const float rs = rsv[s];
;                 float ss = 0.f, mx = 0.f;
; #pragma unroll
;                 for (int bj = 0; bj < 2; ++bj)
; #pragma unroll
;                     for (int n = 0; n < 2; ++n) { const size_t o = off + bj * HALF + n * 16; const f32x4 b = cur.b[bj][n]; f32x4 v;
;                         if constexpr (I8) v = __builtin_convertvector(acc[ai][bj][m][n], f32x4) * rs * sv[bj][n]; else v = acc[ai][bj][m][n];
;                         if (MODE == 1) { const u32x2 pw = cur.pw[bj][n]; const f32x4 pp = (f32x4){bf_lo(pw.x), bf_hi(pw.x), bf_lo(pw.y), bf_hi(pw.y)}; v = sig4(I8 ? v : v * rs) * pp; }
;                         const f32x4 x = b + v; *(f32x4*)(out + o) = x;
;                         if (MODE == 0 && XB) { u32x2 w; w.x = cvt_pk_bf16(x[0], x[1]); w.y = cvt_pk_bf16(x[2], x[3]); *(u32x2*)(XB + o) = w; ss += (x[0] * x[0] + x[1] * x[1]) + (x[2] * x[2] + x[3] * x[3]);
;                             if (RM) mx = fmaxf(fmaxf(mx, fmaxf(fabsf(x[0]), fabsf(x[1]))), fmaxf(fabsf(x[2]), fabsf(x[3]))); } }
;                 if (MODE == 0 && XB) { ss += __shfl_xor(ss, 16); ss += __shfl_xor(ss, 32); if (fq == 0) unsafeAtomicAdd(SS + r, ss);
;                     if (RM) { mx = fmaxf(mx, __shfl_xor(mx, 16)); mx = fmaxf(mx, __shfl_xor(mx, 32)); if (fq == 0) atomicMax(RM + r, __builtin_bit_cast(unsigned, mx)); } }
;                 cur = nxt; }
	v_pk_add_f32 v[110:111], v[110:111], v[146:147]
	v_pk_add_f32 v[112:113], v[112:113], v[148:149]
	v_pk_add_f32 v[106:107], v[106:107], v[150:151]
	v_pk_add_f32 v[108:109], v[108:109], v[152:153]
	v_pk_add_f32 v[102:103], v[102:103], v[154:155]
	v_pk_add_f32 v[104:105], v[104:105], v[156:157]
	v_pk_add_f32 v[98:99], v[98:99], v[158:159]
	v_pk_add_f32 v[100:101], v[100:101], v[160:161]
	v_add_u32_e32 v162, 0x4000, v246
	global_load_dwordx4 v[146:149], v162, s[98:99] offset:0
	global_load_dwordx4 v[150:153], v162, s[98:99] offset:1024
	global_load_dwordx4 v[154:157], v162, s[98:99] offset:2048
	global_load_dwordx4 v[158:161], v162, s[98:99] offset:3072
	v_add_u32_e32 v163, 0x1000, v246
	v_add_u32_e32 v190, 0x20000, v250
	global_store_dwordx4 v163, v[110:113], s[98:99] offset:0
	v_cvt_pk_bf16_f32 v182, v110, v111
	v_cvt_pk_bf16_f32 v183, v112, v113
	v_mul_f32_e32 v166, v111, v111
	v_mul_f32_e32 v167, v113, v113
	v_fmac_f32_e32 v166, v110, v110
	v_fmac_f32_e32 v167, v112, v112
	v_add_f32_e32 v164, v166, v167
	v_max3_f32 v165, |v110|, |v111|, 0
	v_max3_f32 v165, |v112|, |v113|, v165
	global_store_dwordx4 v163, v[106:109], s[98:99] offset:1024
	v_cvt_pk_bf16_f32 v184, v106, v107
	v_cvt_pk_bf16_f32 v185, v108, v109
	v_mul_f32_e32 v166, v107, v107
	v_mul_f32_e32 v167, v109, v109
	v_fmac_f32_e32 v166, v106, v106
	v_fmac_f32_e32 v167, v108, v108
	v_permlane16_swap_b32_e32 v182, v184
	v_permlane16_swap_b32_e32 v183, v185
	v_add_f32_e32 v166, v166, v167
	v_add_f32_e32 v164, v164, v166
	v_max3_f32 v165, |v106|, |v107|, v165
	v_max3_f32 v165, |v108|, |v109|, v165
	global_store_dwordx4 v190, v[182:185], s[52:53] offset:0
	global_store_dwordx4 v163, v[102:105], s[98:99] offset:2048
	v_cvt_pk_bf16_f32 v186, v102, v103
	v_cvt_pk_bf16_f32 v187, v104, v105
	v_mul_f32_e32 v166, v103, v103
	v_mul_f32_e32 v167, v105, v105
	v_fmac_f32_e32 v166, v102, v102
	v_fmac_f32_e32 v167, v104, v104
	v_add_f32_e32 v166, v166, v167
	v_add_f32_e32 v164, v164, v166
	v_max3_f32 v165, |v102|, |v103|, v165
	v_max3_f32 v165, |v104|, |v105|, v165
	global_store_dwordx4 v163, v[98:101], s[98:99] offset:3072
	v_cvt_pk_bf16_f32 v188, v98, v99
	v_cvt_pk_bf16_f32 v189, v100, v101
	v_mul_f32_e32 v166, v99, v99
	v_mul_f32_e32 v167, v101, v101
	v_fmac_f32_e32 v166, v98, v98
	v_fmac_f32_e32 v167, v100, v100
	v_permlane16_swap_b32_e32 v186, v188
	v_permlane16_swap_b32_e32 v187, v189
	v_add_f32_e32 v166, v166, v167
	v_add_f32_e32 v164, v164, v166
	v_max3_f32 v165, |v98|, |v99|, v165
	v_max3_f32 v165, |v100|, |v101|, v165
	global_store_dwordx4 v190, v[186:189], s[52:53] offset:256
	ds_bpermute_b32 v168, v252, v164
	ds_bpermute_b32 v169, v252, v165
	s_waitcnt lgkmcnt(0)
	v_add_f32_e32 v164, v164, v168
	v_max_f32_e32 v165, v165, v169
	ds_bpermute_b32 v168, v253, v164
	ds_bpermute_b32 v169, v253, v165
	s_waitcnt lgkmcnt(0)
	v_add_f32_e32 v164, v164, v168
	v_max_f32_e32 v165, v165, v169
	s_mov_b64 exec, s[6:7]
	global_atomic_add_f32 v251, v164, s[10:11] offset:64
	global_atomic_umax v251, v165, s[12:13] offset:64
	s_mov_b64 exec, -1
	s_waitcnt vmcnt(24)
	v_pk_add_f32 v[94:95], v[94:95], v[196:197]
	v_pk_add_f32 v[96:97], v[96:97], v[198:199]
	v_pk_add_f32 v[90:91], v[90:91], v[200:201]
	v_pk_add_f32 v[92:93], v[92:93], v[202:203]
	v_pk_add_f32 v[86:87], v[86:87], v[204:205]
	v_pk_add_f32 v[88:89], v[88:89], v[206:207]
	v_pk_add_f32 v[82:83], v[82:83], v[208:209]
	v_pk_add_f32 v[84:85], v[84:85], v[210:211]
	v_add_u32_e32 v162, 0x5000, v246
	global_load_dwordx4 v[196:199], v162, s[98:99] offset:0
	global_load_dwordx4 v[200:203], v162, s[98:99] offset:1024
	global_load_dwordx4 v[204:207], v162, s[98:99] offset:2048
	global_load_dwordx4 v[208:211], v162, s[98:99] offset:3072
	v_add_u32_e32 v163, 0x2000, v246
	v_add_u32_e32 v190, 0x40000, v250
	global_store_dwordx4 v163, v[94:97], s[98:99] offset:0
	v_cvt_pk_bf16_f32 v182, v94, v95
	v_cvt_pk_bf16_f32 v183, v96, v97
	v_mul_f32_e32 v166, v95, v95
	v_mul_f32_e32 v167, v97, v97
	v_fmac_f32_e32 v166, v94, v94
	v_fmac_f32_e32 v167, v96, v96
	v_add_f32_e32 v164, v166, v167
	v_max3_f32 v165, |v94|, |v95|, 0
	v_max3_f32 v165, |v96|, |v97|, v165
	global_store_dwordx4 v163, v[90:93], s[98:99] offset:1024
	v_cvt_pk_bf16_f32 v184, v90, v91
	v_cvt_pk_bf16_f32 v185, v92, v93
	v_mul_f32_e32 v166, v91, v91
	v_mul_f32_e32 v167, v93, v93
	v_fmac_f32_e32 v166, v90, v90
	v_fmac_f32_e32 v167, v92, v92
	v_permlane16_swap_b32_e32 v182, v184
	v_permlane16_swap_b32_e32 v183, v185
	v_add_f32_e32 v166, v166, v167
	v_add_f32_e32 v164, v164, v166
	v_max3_f32 v165, |v90|, |v91|, v165
	v_max3_f32 v165, |v92|, |v93|, v165
	global_store_dwordx4 v190, v[182:185], s[52:53] offset:0
	global_store_dwordx4 v163, v[86:89], s[98:99] offset:2048
	v_cvt_pk_bf16_f32 v186, v86, v87
	v_cvt_pk_bf16_f32 v187, v88, v89
	v_mul_f32_e32 v166, v87, v87
	v_mul_f32_e32 v167, v89, v89
	v_fmac_f32_e32 v166, v86, v86
	v_fmac_f32_e32 v167, v88, v88
	v_add_f32_e32 v166, v166, v167
	v_add_f32_e32 v164, v164, v166
	v_max3_f32 v165, |v86|, |v87|, v165
	v_max3_f32 v165, |v88|, |v89|, v165
	global_store_dwordx4 v163, v[82:85], s[98:99] offset:3072
	v_cvt_pk_bf16_f32 v188, v82, v83
	v_cvt_pk_bf16_f32 v189, v84, v85
	v_mul_f32_e32 v166, v83, v83
	v_mul_f32_e32 v167, v85, v85
	v_fmac_f32_e32 v166, v82, v82
	v_fmac_f32_e32 v167, v84, v84
	v_permlane16_swap_b32_e32 v186, v188
	v_permlane16_swap_b32_e32 v187, v189
	v_add_f32_e32 v166, v166, v167
	v_add_f32_e32 v164, v164, v166
	v_max3_f32 v165, |v82|, |v83|, v165
	v_max3_f32 v165, |v84|, |v85|, v165
	global_store_dwordx4 v190, v[186:189], s[52:53] offset:256
	ds_bpermute_b32 v168, v252, v164
	ds_bpermute_b32 v169, v252, v165
	s_waitcnt lgkmcnt(0)
; __device__ __forceinline__ unsigned cvt_pk_bf16(float lo, float hi) { unsigned r; asm volatile("s_nop 0\n\tv_cvt_pk_bf16_f32 %0, %1, %2" : "=v"(r) : "v"(lo), "v"(hi)); return r; }
; __device__ __forceinline__ f32x4 sig4(const f32x4 v) { return (f32x4){sigmoidf_(v[0]), sigmoidf_(v[1]), sigmoidf_(v[2]), sigmoidf_(v[3])}; }
;     __device__ __forceinline__ void operator()(const typename AccT<I8>::type (&acc)[2][2][4][2], const Unit& u, int wr, int wc, int fr, int fq) const {
;     ...
;         for (int s = 0; s < 8; ++s) { const int ai = s >> 2, m = s & 3; const int r = row0 + ai * HALF + m * 16; const size_t off = (size_t)r * 4096 + col0;
;                 if (s + 1 < 8) load_row(nxt, (size_t)(row0 + ((s + 1) >> 2) * HALF + ((s + 1) & 3) * 16) * 4096 + col0);
;                 const float rs = rsv[s];
;                 float ss = 0.f, mx = 0.f;
; #pragma unroll
;                 for (int bj = 0; bj < 2; ++bj)
; #pragma unroll
;                     for (int n = 0; n < 2; ++n) { const size_t o = off + bj * HALF + n * 16; const f32x4 b = cur.b[bj][n]; f32x4 v;
;                         if constexpr (I8) v = __builtin_convertvector(acc[ai][bj][m][n], f32x4) * rs * sv[bj][n]; else v = acc[ai][bj][m][n];
;                         if (MODE == 1) { const u32x2 pw = cur.pw[bj][n]; const f32x4 pp = (f32x4){bf_lo(pw.x), bf_hi(pw.x), bf_lo(pw.y), bf_hi(pw.y)}; v = sig4(I8 ? v : v * rs) * pp; }
;                         const f32x4 x = b + v; *(f32x4*)(out + o) = x;
;                         if (MODE == 0 && XB) { u32x2 w; w.x = cvt_pk_bf16(x[0], x[1]); w.y = cvt_pk_bf16(x[2], x[3]); *(u32x2*)(XB + o) = w; ss += (x[0] * x[0] + x[1] * x[1]) + (x[2] * x[2] + x[3] * x[3]);
;                             if (RM) mx = fmaxf(fmaxf(mx, fmaxf(fabsf(x[0]), fabsf(x[1]))), fmaxf(fabsf(x[2]), fabsf(x[3]))); } }
;                 if (MODE == 0 && XB) { ss += __shfl_xor(ss, 16); ss += __shfl_xor(ss, 32); if (fq == 0) unsafeAtomicAdd(SS + r, ss);
;                     if (RM) { mx = fmaxf(mx, __shfl_xor(mx, 16)); mx = fmaxf(mx, __shfl_xor(mx, 32)); if (fq == 0) atomicMax(RM + r, __builtin_bit_cast(unsigned, mx)); } }
;                 cur = nxt; }
	v_add_f32_e32 v164, v164, v168
	v_max_f32_e32 v165, v165, v169
	ds_bpermute_b32 v168, v253, v164
	ds_bpermute_b32 v169, v253, v165
	s_waitcnt lgkmcnt(0)
	v_add_f32_e32 v164, v164, v168
	v_max_f32_e32 v165, v165, v169
	s_mov_b64 exec, s[6:7]
	global_atomic_add_f32 v251, v164, s[10:11] offset:128
	global_atomic_umax v251, v165, s[12:13] offset:128
	s_mov_b64 exec, -1
	s_waitcnt vmcnt(32)
	v_pk_add_f32 v[78:79], v[78:79], v[130:131]
	v_pk_add_f32 v[80:81], v[80:81], v[132:133]
	v_pk_add_f32 v[74:75], v[74:75], v[134:135]
	v_pk_add_f32 v[76:77], v[76:77], v[136:137]
	v_pk_add_f32 v[70:71], v[70:71], v[138:139]
	v_pk_add_f32 v[72:73], v[72:73], v[140:141]
	v_pk_add_f32 v[66:67], v[66:67], v[142:143]
	v_pk_add_f32 v[68:69], v[68:69], v[144:145]
	v_add_u32_e32 v162, 0x6000, v246
	global_load_dwordx4 v[130:133], v162, s[98:99] offset:0
	global_load_dwordx4 v[134:137], v162, s[98:99] offset:1024
	global_load_dwordx4 v[138:141], v162, s[98:99] offset:2048
	global_load_dwordx4 v[142:145], v162, s[98:99] offset:3072
	v_add_u32_e32 v163, 0x3000, v246
	v_add_u32_e32 v190, 0x60000, v250
	global_store_dwordx4 v163, v[78:81], s[98:99] offset:0
	v_cvt_pk_bf16_f32 v182, v78, v79
	v_cvt_pk_bf16_f32 v183, v80, v81
	v_mul_f32_e32 v166, v79, v79
	v_mul_f32_e32 v167, v81, v81
	v_fmac_f32_e32 v166, v78, v78
	v_fmac_f32_e32 v167, v80, v80
	v_add_f32_e32 v164, v166, v167
	v_max3_f32 v165, |v78|, |v79|, 0
	v_max3_f32 v165, |v80|, |v81|, v165
	global_store_dwordx4 v163, v[74:77], s[98:99] offset:1024
	v_cvt_pk_bf16_f32 v184, v74, v75
	v_cvt_pk_bf16_f32 v185, v76, v77
	v_mul_f32_e32 v166, v75, v75
	v_mul_f32_e32 v167, v77, v77
	v_fmac_f32_e32 v166, v74, v74
	v_fmac_f32_e32 v167, v76, v76
	v_permlane16_swap_b32_e32 v182, v184
	v_permlane16_swap_b32_e32 v183, v185
	v_add_f32_e32 v166, v166, v167
	v_add_f32_e32 v164, v164, v166
	v_max3_f32 v165, |v74|, |v75|, v165
	v_max3_f32 v165, |v76|, |v77|, v165
	global_store_dwordx4 v190, v[182:185], s[52:53] offset:0
	global_store_dwordx4 v163, v[70:73], s[98:99] offset:2048
	v_cvt_pk_bf16_f32 v186, v70, v71
	v_cvt_pk_bf16_f32 v187, v72, v73
	v_mul_f32_e32 v166, v71, v71
	v_mul_f32_e32 v167, v73, v73
	v_fmac_f32_e32 v166, v70, v70
	v_fmac_f32_e32 v167, v72, v72
	v_add_f32_e32 v166, v166, v167
	v_add_f32_e32 v164, v164, v166
	v_max3_f32 v165, |v70|, |v71|, v165
	v_max3_f32 v165, |v72|, |v73|, v165
	global_store_dwordx4 v163, v[66:69], s[98:99] offset:3072
	v_cvt_pk_bf16_f32 v188, v66, v67
	v_cvt_pk_bf16_f32 v189, v68, v69
	v_mul_f32_e32 v166, v67, v67
	v_mul_f32_e32 v167, v69, v69
	v_fmac_f32_e32 v166, v66, v66
	v_fmac_f32_e32 v167, v68, v68
	v_permlane16_swap_b32_e32 v186, v188
	v_permlane16_swap_b32_e32 v187, v189
	v_add_f32_e32 v166, v166, v167
	v_add_f32_e32 v164, v164, v166
	v_max3_f32 v165, |v66|, |v67|, v165
	v_max3_f32 v165, |v68|, |v69|, v165
	global_store_dwordx4 v190, v[186:189], s[52:53] offset:256
	ds_bpermute_b32 v168, v252, v164
	ds_bpermute_b32 v169, v252, v165
	s_waitcnt lgkmcnt(0)
	v_add_f32_e32 v164, v164, v168
	v_max_f32_e32 v165, v165, v169
	ds_bpermute_b32 v168, v253, v164
	ds_bpermute_b32 v169, v253, v165
	s_waitcnt lgkmcnt(0)
	v_add_f32_e32 v164, v164, v168
	v_max_f32_e32 v165, v165, v169
	s_mov_b64 exec, s[6:7]
	global_atomic_add_f32 v251, v164, s[10:11] offset:192
	global_atomic_umax v251, v165, s[12:13] offset:192
	s_mov_b64 exec, -1
	s_waitcnt vmcnt(32)
	v_pk_add_f32 v[62:63], v[62:63], v[146:147]
	v_pk_add_f32 v[64:65], v[64:65], v[148:149]
	v_pk_add_f32 v[58:59], v[58:59], v[150:151]
	v_pk_add_f32 v[60:61], v[60:61], v[152:153]
	v_pk_add_f32 v[54:55], v[54:55], v[154:155]
	v_pk_add_f32 v[56:57], v[56:57], v[156:157]
	v_pk_add_f32 v[50:51], v[50:51], v[158:159]
	v_pk_add_f32 v[52:53], v[52:53], v[160:161]
	v_add_u32_e32 v162, 0x7000, v246
	global_load_dwordx4 v[146:149], v162, s[98:99] offset:0
	global_load_dwordx4 v[150:153], v162, s[98:99] offset:1024
	global_load_dwordx4 v[154:157], v162, s[98:99] offset:2048
	global_load_dwordx4 v[158:161], v162, s[98:99] offset:3072
	v_add_u32_e32 v163, 0x4000, v246
	v_add_u32_e32 v190, 0x100000, v250
	global_store_dwordx4 v163, v[62:65], s[98:99] offset:0
	v_cvt_pk_bf16_f32 v182, v62, v63
	v_cvt_pk_bf16_f32 v183, v64, v65
	v_mul_f32_e32 v166, v63, v63
	v_mul_f32_e32 v167, v65, v65
	v_fmac_f32_e32 v166, v62, v62
	v_fmac_f32_e32 v167, v64, v64
	v_add_f32_e32 v164, v166, v167
	v_max3_f32 v165, |v62|, |v63|, 0
	v_max3_f32 v165, |v64|, |v65|, v165
	global_store_dwordx4 v163, v[58:61], s[98:99] offset:1024
	v_cvt_pk_bf16_f32 v184, v58, v59
	v_cvt_pk_bf16_f32 v185, v60, v61
	v_mul_f32_e32 v166, v59, v59
	v_mul_f32_e32 v167, v61, v61
	v_fmac_f32_e32 v166, v58, v58
	v_fmac_f32_e32 v167, v60, v60
	v_permlane16_swap_b32_e32 v182, v184
	v_permlane16_swap_b32_e32 v183, v185
	v_add_f32_e32 v166, v166, v167
	v_add_f32_e32 v164, v164, v166
	v_max3_f32 v165, |v58|, |v59|, v165
	v_max3_f32 v165, |v60|, |v61|, v165
	global_store_dwordx4 v190, v[182:185], s[52:53] offset:0
	global_store_dwordx4 v163, v[54:57], s[98:99] offset:2048
	v_cvt_pk_bf16_f32 v186, v54, v55
	v_cvt_pk_bf16_f32 v187, v56, v57
	v_mul_f32_e32 v166, v55, v55
	v_mul_f32_e32 v167, v57, v57
	v_fmac_f32_e32 v166, v54, v54
	v_fmac_f32_e32 v167, v56, v56
	v_add_f32_e32 v166, v166, v167
	v_add_f32_e32 v164, v164, v166
	v_max3_f32 v165, |v54|, |v55|, v165
	v_max3_f32 v165, |v56|, |v57|, v165
	global_store_dwordx4 v163, v[50:53], s[98:99] offset:3072
	v_cvt_pk_bf16_f32 v188, v50, v51
	v_cvt_pk_bf16_f32 v189, v52, v53
	v_mul_f32_e32 v166, v51, v51
	v_mul_f32_e32 v167, v53, v53
	v_fmac_f32_e32 v166, v50, v50
	v_fmac_f32_e32 v167, v52, v52
	v_permlane16_swap_b32_e32 v186, v188
	v_permlane16_swap_b32_e32 v187, v189
	v_add_f32_e32 v166, v166, v167
	v_add_f32_e32 v164, v164, v166
	v_max3_f32 v165, |v50|, |v51|, v165
	v_max3_f32 v165, |v52|, |v53|, v165
	global_store_dwordx4 v190, v[186:189], s[52:53] offset:256
	ds_bpermute_b32 v168, v252, v164
	ds_bpermute_b32 v169, v252, v165
	s_waitcnt lgkmcnt(0)
; __device__ __forceinline__ unsigned cvt_pk_bf16(float lo, float hi) { unsigned r; asm volatile("s_nop 0\n\tv_cvt_pk_bf16_f32 %0, %1, %2" : "=v"(r) : "v"(lo), "v"(hi)); return r; }
; __device__ __forceinline__ f32x4 sig4(const f32x4 v) { return (f32x4){sigmoidf_(v[0]), sigmoidf_(v[1]), sigmoidf_(v[2]), sigmoidf_(v[3])}; }
;     __device__ __forceinline__ void operator()(const typename AccT<I8>::type (&acc)[2][2][4][2], const Unit& u, int wr, int wc, int fr, int fq) const {
;     ...
;         for (int s = 0; s < 8; ++s) { const int ai = s >> 2, m = s & 3; const int r = row0 + ai * HALF + m * 16; const size_t off = (size_t)r * 4096 + col0;
;                 if (s + 1 < 8) load_row(nxt, (size_t)(row0 + ((s + 1) >> 2) * HALF + ((s + 1) & 3) * 16) * 4096 + col0);
;                 const float rs = rsv[s];
;                 float ss = 0.f, mx = 0.f;
; #pragma unroll
;                 for (int bj = 0; bj < 2; ++bj)
; #pragma unroll
;                     for (int n = 0; n < 2; ++n) { const size_t o = off + bj * HALF + n * 16; const f32x4 b = cur.b[bj][n]; f32x4 v;
;                         if constexpr (I8) v = __builtin_convertvector(acc[ai][bj][m][n], f32x4) * rs * sv[bj][n]; else v = acc[ai][bj][m][n];
;                         if (MODE == 1) { const u32x2 pw = cur.pw[bj][n]; const f32x4 pp = (f32x4){bf_lo(pw.x), bf_hi(pw.x), bf_lo(pw.y), bf_hi(pw.y)}; v = sig4(I8 ? v : v * rs) * pp; }
;                         const f32x4 x = b + v; *(f32x4*)(out + o) = x;
;                         if (MODE == 0 && XB) { u32x2 w; w.x = cvt_pk_bf16(x[0], x[1]); w.y = cvt_pk_bf16(x[2], x[3]); *(u32x2*)(XB + o) = w; ss += (x[0] * x[0] + x[1] * x[1]) + (x[2] * x[2] + x[3] * x[3]);
;                             if (RM) mx = fmaxf(fmaxf(mx, fmaxf(fabsf(x[0]), fabsf(x[1]))), fmaxf(fabsf(x[2]), fabsf(x[3]))); } }
;                 if (MODE == 0 && XB) { ss += __shfl_xor(ss, 16); ss += __shfl_xor(ss, 32); if (fq == 0) unsafeAtomicAdd(SS + r, ss);
;                     if (RM) { mx = fmaxf(mx, __shfl_xor(mx, 16)); mx = fmaxf(mx, __shfl_xor(mx, 32)); if (fq == 0) atomicMax(RM + r, __builtin_bit_cast(unsigned, mx)); } }
;                 cur = nxt; }
	v_add_f32_e32 v164, v164, v168
	v_max_f32_e32 v165, v165, v169
	ds_bpermute_b32 v168, v253, v164
	ds_bpermute_b32 v169, v253, v165
	s_waitcnt lgkmcnt(0)
	v_add_f32_e32 v164, v164, v168
	v_max_f32_e32 v165, v165, v169
	s_mov_b64 exec, s[6:7]
	global_atomic_add_f32 v251, v164, s[10:11] offset:512
	global_atomic_umax v251, v165, s[12:13] offset:512
	s_mov_b64 exec, -1
	s_waitcnt vmcnt(32)
	v_pk_add_f32 v[46:47], v[46:47], v[196:197]
	v_pk_add_f32 v[48:49], v[48:49], v[198:199]
	v_pk_add_f32 v[42:43], v[42:43], v[200:201]
	v_pk_add_f32 v[44:45], v[44:45], v[202:203]
	v_pk_add_f32 v[38:39], v[38:39], v[204:205]
	v_pk_add_f32 v[40:41], v[40:41], v[206:207]
	v_pk_add_f32 v[34:35], v[34:35], v[208:209]
	v_pk_add_f32 v[36:37], v[36:37], v[210:211]
	v_add_u32_e32 v163, 0x5000, v246
	v_add_u32_e32 v190, 0x120000, v250
	global_store_dwordx4 v163, v[46:49], s[98:99] offset:0
	v_cvt_pk_bf16_f32 v182, v46, v47
	v_cvt_pk_bf16_f32 v183, v48, v49
	v_mul_f32_e32 v166, v47, v47
	v_mul_f32_e32 v167, v49, v49
	v_fmac_f32_e32 v166, v46, v46
	v_fmac_f32_e32 v167, v48, v48
	v_add_f32_e32 v164, v166, v167
	v_max3_f32 v165, |v46|, |v47|, 0
	v_max3_f32 v165, |v48|, |v49|, v165
	global_store_dwordx4 v163, v[42:45], s[98:99] offset:1024
	v_cvt_pk_bf16_f32 v184, v42, v43
	v_cvt_pk_bf16_f32 v185, v44, v45
	v_mul_f32_e32 v166, v43, v43
	v_mul_f32_e32 v167, v45, v45
	v_fmac_f32_e32 v166, v42, v42
	v_fmac_f32_e32 v167, v44, v44
	v_permlane16_swap_b32_e32 v182, v184
	v_permlane16_swap_b32_e32 v183, v185
	v_add_f32_e32 v166, v166, v167
	v_add_f32_e32 v164, v164, v166
	v_max3_f32 v165, |v42|, |v43|, v165
	v_max3_f32 v165, |v44|, |v45|, v165
	global_store_dwordx4 v190, v[182:185], s[52:53] offset:0
	global_store_dwordx4 v163, v[38:41], s[98:99] offset:2048
	v_cvt_pk_bf16_f32 v186, v38, v39
	v_cvt_pk_bf16_f32 v187, v40, v41
	v_mul_f32_e32 v166, v39, v39
	v_mul_f32_e32 v167, v41, v41
	v_fmac_f32_e32 v166, v38, v38
	v_fmac_f32_e32 v167, v40, v40
	v_add_f32_e32 v166, v166, v167
	v_add_f32_e32 v164, v164, v166
	v_max3_f32 v165, |v38|, |v39|, v165
	v_max3_f32 v165, |v40|, |v41|, v165
	global_store_dwordx4 v163, v[34:37], s[98:99] offset:3072
	v_cvt_pk_bf16_f32 v188, v34, v35
	v_cvt_pk_bf16_f32 v189, v36, v37
	v_mul_f32_e32 v166, v35, v35
	v_mul_f32_e32 v167, v37, v37
	v_fmac_f32_e32 v166, v34, v34
	v_fmac_f32_e32 v167, v36, v36
	v_permlane16_swap_b32_e32 v186, v188
	v_permlane16_swap_b32_e32 v187, v189
	v_add_f32_e32 v166, v166, v167
	v_add_f32_e32 v164, v164, v166
	v_max3_f32 v165, |v34|, |v35|, v165
	v_max3_f32 v165, |v36|, |v37|, v165
	global_store_dwordx4 v190, v[186:189], s[52:53] offset:256
	ds_bpermute_b32 v168, v252, v164
	ds_bpermute_b32 v169, v252, v165
	s_waitcnt lgkmcnt(0)
	v_add_f32_e32 v164, v164, v168
	v_max_f32_e32 v165, v165, v169
	ds_bpermute_b32 v168, v253, v164
	ds_bpermute_b32 v169, v253, v165
	s_waitcnt lgkmcnt(0)
	v_add_f32_e32 v164, v164, v168
	v_max_f32_e32 v165, v165, v169
	s_mov_b64 exec, s[6:7]
	global_atomic_add_f32 v251, v164, s[10:11] offset:576
	global_atomic_umax v251, v165, s[12:13] offset:576
	s_mov_b64 exec, -1
	s_waitcnt vmcnt(28)
; __device__ __forceinline__ unsigned cvt_pk_bf16(float lo, float hi) { unsigned r; asm volatile("s_nop 0\n\tv_cvt_pk_bf16_f32 %0, %1, %2" : "=v"(r) : "v"(lo), "v"(hi)); return r; }
; __device__ __forceinline__ f32x4 sig4(const f32x4 v) { return (f32x4){sigmoidf_(v[0]), sigmoidf_(v[1]), sigmoidf_(v[2]), sigmoidf_(v[3])}; }
;     __device__ __forceinline__ void operator()(const typename AccT<I8>::type (&acc)[2][2][4][2], const Unit& u, int wr, int wc, int fr, int fq) const {
;     ...
;         for (int s = 0; s < 8; ++s) { const int ai = s >> 2, m = s & 3; const int r = row0 + ai * HALF + m * 16; const size_t off = (size_t)r * 4096 + col0;
;                 if (s + 1 < 8) load_row(nxt, (size_t)(row0 + ((s + 1) >> 2) * HALF + ((s + 1) & 3) * 16) * 4096 + col0);
;                 const float rs = rsv[s];
;                 float ss = 0.f, mx = 0.f;
; #pragma unroll
;                 for (int bj = 0; bj < 2; ++bj)
; #pragma unroll
;                     for (int n = 0; n < 2; ++n) { const size_t o = off + bj * HALF + n * 16; const f32x4 b = cur.b[bj][n]; f32x4 v;
;                         if constexpr (I8) v = __builtin_convertvector(acc[ai][bj][m][n], f32x4) * rs * sv[bj][n]; else v = acc[ai][bj][m][n];
;                         if (MODE == 1) { const u32x2 pw = cur.pw[bj][n]; const f32x4 pp = (f32x4){bf_lo(pw.x), bf_hi(pw.x), bf_lo(pw.y), bf_hi(pw.y)}; v = sig4(I8 ? v : v * rs) * pp; }
;                         const f32x4 x = b + v; *(f32x4*)(out + o) = x;
;                         if (MODE == 0 && XB) { u32x2 w; w.x = cvt_pk_bf16(x[0], x[1]); w.y = cvt_pk_bf16(x[2], x[3]); *(u32x2*)(XB + o) = w; ss += (x[0] * x[0] + x[1] * x[1]) + (x[2] * x[2] + x[3] * x[3]);
;                             if (RM) mx = fmaxf(fmaxf(mx, fmaxf(fabsf(x[0]), fabsf(x[1]))), fmaxf(fabsf(x[2]), fabsf(x[3]))); } }
;                 if (MODE == 0 && XB) { ss += __shfl_xor(ss, 16); ss += __shfl_xor(ss, 32); if (fq == 0) unsafeAtomicAdd(SS + r, ss);
;                     if (RM) { mx = fmaxf(mx, __shfl_xor(mx, 16)); mx = fmaxf(mx, __shfl_xor(mx, 32)); if (fq == 0) atomicMax(RM + r, __builtin_bit_cast(unsigned, mx)); } }
;                 cur = nxt; }
	v_pk_add_f32 v[30:31], v[30:31], v[130:131]
	v_pk_add_f32 v[32:33], v[32:33], v[132:133]
	v_pk_add_f32 v[26:27], v[26:27], v[134:135]
	v_pk_add_f32 v[28:29], v[28:29], v[136:137]
	v_pk_add_f32 v[18:19], v[18:19], v[138:139]
	v_pk_add_f32 v[20:21], v[20:21], v[140:141]
	v_pk_add_f32 v[14:15], v[14:15], v[142:143]
	v_pk_add_f32 v[16:17], v[16:17], v[144:145]
	v_add_u32_e32 v163, 0x6000, v246
	v_add_u32_e32 v190, 0x140000, v250
	global_store_dwordx4 v163, v[30:33], s[98:99] offset:0
	v_cvt_pk_bf16_f32 v182, v30, v31
	v_cvt_pk_bf16_f32 v183, v32, v33
	v_mul_f32_e32 v166, v31, v31
	v_mul_f32_e32 v167, v33, v33
	v_fmac_f32_e32 v166, v30, v30
	v_fmac_f32_e32 v167, v32, v32
	v_add_f32_e32 v164, v166, v167
	v_max3_f32 v165, |v30|, |v31|, 0
	v_max3_f32 v165, |v32|, |v33|, v165
	global_store_dwordx4 v163, v[26:29], s[98:99] offset:1024
	v_cvt_pk_bf16_f32 v184, v26, v27
	v_cvt_pk_bf16_f32 v185, v28, v29
	v_mul_f32_e32 v166, v27, v27
	v_mul_f32_e32 v167, v29, v29
	v_fmac_f32_e32 v166, v26, v26
	v_fmac_f32_e32 v167, v28, v28
	v_permlane16_swap_b32_e32 v182, v184
	v_permlane16_swap_b32_e32 v183, v185
	v_add_f32_e32 v166, v166, v167
	v_add_f32_e32 v164, v164, v166
	v_max3_f32 v165, |v26|, |v27|, v165
	v_max3_f32 v165, |v28|, |v29|, v165
	global_store_dwordx4 v190, v[182:185], s[52:53] offset:0
	global_store_dwordx4 v163, v[18:21], s[98:99] offset:2048
	v_cvt_pk_bf16_f32 v186, v18, v19
	v_cvt_pk_bf16_f32 v187, v20, v21
	v_mul_f32_e32 v166, v19, v19
	v_mul_f32_e32 v167, v21, v21
	v_fmac_f32_e32 v166, v18, v18
	v_fmac_f32_e32 v167, v20, v20
	v_add_f32_e32 v166, v166, v167
	v_add_f32_e32 v164, v164, v166
	v_max3_f32 v165, |v18|, |v19|, v165
	v_max3_f32 v165, |v20|, |v21|, v165
	global_store_dwordx4 v163, v[14:17], s[98:99] offset:3072
	v_cvt_pk_bf16_f32 v188, v14, v15
	v_cvt_pk_bf16_f32 v189, v16, v17
	v_mul_f32_e32 v166, v15, v15
	v_mul_f32_e32 v167, v17, v17
	v_fmac_f32_e32 v166, v14, v14
	v_fmac_f32_e32 v167, v16, v16
	v_permlane16_swap_b32_e32 v186, v188
	v_permlane16_swap_b32_e32 v187, v189
	v_add_f32_e32 v166, v166, v167
	v_add_f32_e32 v164, v164, v166
	v_max3_f32 v165, |v14|, |v15|, v165
	v_max3_f32 v165, |v16|, |v17|, v165
	global_store_dwordx4 v190, v[186:189], s[52:53] offset:256
	ds_bpermute_b32 v168, v252, v164
	ds_bpermute_b32 v169, v252, v165
	s_waitcnt lgkmcnt(0)
	v_add_f32_e32 v164, v164, v168
	v_max_f32_e32 v165, v165, v169
	ds_bpermute_b32 v168, v253, v164
	ds_bpermute_b32 v169, v253, v165
	s_waitcnt lgkmcnt(0)
	v_add_f32_e32 v164, v164, v168
	v_max_f32_e32 v165, v165, v169
	s_mov_b64 exec, s[6:7]
	global_atomic_add_f32 v251, v164, s[10:11] offset:640
	global_atomic_umax v251, v165, s[12:13] offset:640
	s_mov_b64 exec, -1
	s_waitcnt vmcnt(24)
	v_pk_add_f32 v[22:23], v[22:23], v[146:147]
	v_pk_add_f32 v[24:25], v[24:25], v[148:149]
	v_pk_add_f32 v[10:11], v[10:11], v[150:151]
	v_pk_add_f32 v[12:13], v[12:13], v[152:153]
	v_pk_add_f32 v[6:7], v[6:7], v[154:155]
	v_pk_add_f32 v[8:9], v[8:9], v[156:157]
	v_pk_add_f32 v[2:3], v[2:3], v[158:159]
	v_pk_add_f32 v[4:5], v[4:5], v[160:161]
	v_add_u32_e32 v163, 0x7000, v246
	v_add_u32_e32 v190, 0x160000, v250
	global_store_dwordx4 v163, v[22:25], s[98:99] offset:0
	v_cvt_pk_bf16_f32 v182, v22, v23
	v_cvt_pk_bf16_f32 v183, v24, v25
	v_mul_f32_e32 v166, v23, v23
	v_mul_f32_e32 v167, v25, v25
	v_fmac_f32_e32 v166, v22, v22
	v_fmac_f32_e32 v167, v24, v24
	v_add_f32_e32 v164, v166, v167
	v_max3_f32 v165, |v22|, |v23|, 0
	v_max3_f32 v165, |v24|, |v25|, v165
	global_store_dwordx4 v163, v[10:13], s[98:99] offset:1024
	v_cvt_pk_bf16_f32 v184, v10, v11
	v_cvt_pk_bf16_f32 v185, v12, v13
	v_mul_f32_e32 v166, v11, v11
	v_mul_f32_e32 v167, v13, v13
	v_fmac_f32_e32 v166, v10, v10
	v_fmac_f32_e32 v167, v12, v12
	v_permlane16_swap_b32_e32 v182, v184
	v_permlane16_swap_b32_e32 v183, v185
	v_add_f32_e32 v166, v166, v167
	v_add_f32_e32 v164, v164, v166
	v_max3_f32 v165, |v10|, |v11|, v165
	v_max3_f32 v165, |v12|, |v13|, v165
	global_store_dwordx4 v190, v[182:185], s[52:53] offset:0
	global_store_dwordx4 v163, v[6:9], s[98:99] offset:2048
	v_cvt_pk_bf16_f32 v186, v6, v7
	v_cvt_pk_bf16_f32 v187, v8, v9
	v_mul_f32_e32 v166, v7, v7
	v_mul_f32_e32 v167, v9, v9
	v_fmac_f32_e32 v166, v6, v6
	v_fmac_f32_e32 v167, v8, v8
	v_add_f32_e32 v166, v166, v167
	v_add_f32_e32 v164, v164, v166
	v_max3_f32 v165, |v6|, |v7|, v165
	v_max3_f32 v165, |v8|, |v9|, v165
	global_store_dwordx4 v163, v[2:5], s[98:99] offset:3072
	v_cvt_pk_bf16_f32 v188, v2, v3
	v_cvt_pk_bf16_f32 v189, v4, v5
	v_mul_f32_e32 v166, v3, v3
	v_mul_f32_e32 v167, v5, v5
	v_fmac_f32_e32 v166, v2, v2
	v_fmac_f32_e32 v167, v4, v4
	v_permlane16_swap_b32_e32 v186, v188
	v_permlane16_swap_b32_e32 v187, v189
	v_add_f32_e32 v166, v166, v167
	v_add_f32_e32 v164, v164, v166
	v_max3_f32 v165, |v2|, |v3|, v165
	v_max3_f32 v165, |v4|, |v5|, v165
	global_store_dwordx4 v190, v[186:189], s[52:53] offset:256
	ds_bpermute_b32 v168, v252, v164
	ds_bpermute_b32 v169, v252, v165
	s_waitcnt lgkmcnt(0)
	v_add_f32_e32 v164, v164, v168
	v_max_f32_e32 v165, v165, v169
	ds_bpermute_b32 v168, v253, v164
	ds_bpermute_b32 v169, v253, v165
	s_waitcnt lgkmcnt(0)
	v_add_f32_e32 v164, v164, v168
	v_max_f32_e32 v165, v165, v169
	s_mov_b64 exec, s[6:7]
	global_atomic_add_f32 v251, v164, s[10:11] offset:704
	global_atomic_umax v251, v165, s[12:13] offset:704
	s_mov_b64 exec, -1
